# v75 + non-temporal hint on the P8 merge-epilogue gate and hbuf loads (read once)
# speedup vs baseline: 1.0051x; 1.0051x over previous
.LBB0_845:
	v_lshl_add_u32 v144, s41, 8, v152
	v_lshl_add_u32 v146, s40, 8, v150
	v_ashrrev_i32_e32 v145, 31, v144
	v_mov_b64_e32 v[148:149], s[12:13]
	v_mad_i64_i32 v[156:157], s[0:1], v146, s38, v[148:149]
	v_lshlrev_b64 v[144:145], 1, v[144:145]
	v_lshl_add_u64 v[160:161], v[156:157], 0, v[144:145]
	global_load_dwordx4 v[156:159], v[160:161], off nt
	v_ashrrev_i32_e32 v147, 31, v146
	v_readlane_b32 s2, v235, 19
	v_lshlrev_b64 v[162:163], 12, v[146:147]
	v_readlane_b32 s3, v235, 20
	v_or_b32_e32 v164, 16, v146
	v_mad_i64_i32 v[166:167], s[0:1], v164, s38, v[148:149]
	v_lshl_add_u64 v[162:163], s[2:3], 0, v[162:163]
	v_lshl_add_u64 v[168:169], v[162:163], 0, v[144:145]
	global_load_dwordx4 v[160:163], v[160:161], off offset:256 nt
	v_lshl_add_u64 v[166:167], v[166:167], 0, v[144:145]
	s_and_b64 vcc, exec, s[4:5]
	s_waitcnt vmcnt(0)
	v_lshlrev_b32_e32 v171, 16, v159
	v_and_b32_e32 v159, 0xffff0000, v159
	v_lshlrev_b32_e32 v147, 16, v156
	v_and_b32_e32 v156, 0xffff0000, v156
	v_lshlrev_b32_e32 v165, 16, v157
	v_and_b32_e32 v157, 0xffff0000, v157
	v_lshlrev_b32_e32 v170, 16, v158
	v_and_b32_e32 v158, 0xffff0000, v158
	v_mul_f32_e32 v159, 0xbfb8aa3b, v159
	v_mul_f32_e32 v147, 0xbfb8aa3b, v147
	v_mul_f32_e32 v156, 0xbfb8aa3b, v156
	v_mul_f32_e32 v165, 0xbfb8aa3b, v165
	v_mul_f32_e32 v157, 0xbfb8aa3b, v157
	v_mul_f32_e32 v170, 0xbfb8aa3b, v170
	v_mul_f32_e32 v158, 0xbfb8aa3b, v158
	v_mul_f32_e32 v171, 0xbfb8aa3b, v171
	v_exp_f32_e32 v159, v159
	v_exp_f32_e32 v147, v147
	v_exp_f32_e32 v156, v156
	v_exp_f32_e32 v165, v165
	v_exp_f32_e32 v157, v157
	v_exp_f32_e32 v170, v170
	v_exp_f32_e32 v158, v158
	v_exp_f32_e32 v171, v171
	v_add_f32_e32 v159, 1.0, v159
	v_add_f32_e32 v147, 1.0, v147
	v_add_f32_e32 v156, 1.0, v156
	v_add_f32_e32 v165, 1.0, v165
	v_add_f32_e32 v157, 1.0, v157
	v_add_f32_e32 v170, 1.0, v170
	v_add_f32_e32 v158, 1.0, v158
	v_add_f32_e32 v171, 1.0, v171
	v_rcp_f32_e32 v159, v159
	v_rcp_f32_e32 v147, v147
	v_rcp_f32_e32 v156, v156
	v_rcp_f32_e32 v165, v165
	v_rcp_f32_e32 v157, v157
	v_rcp_f32_e32 v170, v170
	v_rcp_f32_e32 v158, v158
	v_rcp_f32_e32 v171, v171
	v_mul_f32_e32 v123, v123, v159
	v_mul_f32_e32 v124, v124, v147
	v_mul_f32_e32 v125, v125, v156
	v_mul_f32_e32 v126, v126, v165
	v_mul_f32_e32 v127, v127, v157
	v_mul_f32_e32 v147, v120, v170
	v_mul_f32_e32 v156, v121, v158
	v_mul_f32_e32 v157, v122, v171
	v_cvt_pk_bf16_f32 v120, v124, v125
	v_cvt_pk_bf16_f32 v121, v126, v127
	v_cvt_pk_bf16_f32 v122, v147, v156
	v_cvt_pk_bf16_f32 v123, v157, v123
	global_store_dwordx4 v[168:169], v[120:123], off
	global_load_dwordx4 v[120:123], v[166:167], off nt
	v_lshlrev_b32_e32 v125, 16, v160
	v_and_b32_e32 v147, 0xffff0000, v160
	v_lshlrev_b32_e32 v158, 16, v161
	v_and_b32_e32 v159, 0xffff0000, v161
	v_lshlrev_b32_e32 v160, 16, v162
	v_and_b32_e32 v161, 0xffff0000, v162
	v_lshlrev_b32_e32 v162, 16, v163
	v_and_b32_e32 v163, 0xffff0000, v163
	v_mul_f32_e32 v163, 0xbfb8aa3b, v163
	v_mul_f32_e32 v125, 0xbfb8aa3b, v125
	v_mul_f32_e32 v147, 0xbfb8aa3b, v147
	v_mul_f32_e32 v158, 0xbfb8aa3b, v158
	v_mul_f32_e32 v159, 0xbfb8aa3b, v159
	v_mul_f32_e32 v160, 0xbfb8aa3b, v160
	v_mul_f32_e32 v161, 0xbfb8aa3b, v161
	v_mul_f32_e32 v162, 0xbfb8aa3b, v162
	v_exp_f32_e32 v163, v163
	v_exp_f32_e32 v125, v125
	v_exp_f32_e32 v147, v147
	v_exp_f32_e32 v158, v158
	v_exp_f32_e32 v159, v159
	v_exp_f32_e32 v160, v160
	v_exp_f32_e32 v161, v161
	v_exp_f32_e32 v162, v162
	v_add_f32_e32 v163, 1.0, v163
	v_add_f32_e32 v125, 1.0, v125
	v_add_f32_e32 v147, 1.0, v147
	v_add_f32_e32 v158, 1.0, v158
	v_add_f32_e32 v159, 1.0, v159
	v_add_f32_e32 v160, 1.0, v160
	v_add_f32_e32 v161, 1.0, v161
	v_add_f32_e32 v162, 1.0, v162
	v_rcp_f32_e32 v163, v163
	v_rcp_f32_e32 v125, v125
	v_rcp_f32_e32 v147, v147
	v_rcp_f32_e32 v158, v158
	v_rcp_f32_e32 v159, v159
	v_rcp_f32_e32 v160, v160
	v_rcp_f32_e32 v161, v161
	v_rcp_f32_e32 v162, v162
	v_mul_f32_e32 v115, v115, v163
	v_mul_f32_e32 v116, v116, v125
	v_mul_f32_e32 v117, v117, v147
	v_mul_f32_e32 v118, v118, v158
	v_mul_f32_e32 v119, v119, v159
	v_mul_f32_e32 v125, v112, v160
	v_mul_f32_e32 v147, v113, v161
	v_mul_f32_e32 v158, v114, v162
	v_cvt_pk_bf16_f32 v112, v116, v117
	v_cvt_pk_bf16_f32 v113, v118, v119
	v_cvt_pk_bf16_f32 v114, v125, v147
	v_cvt_pk_bf16_f32 v115, v158, v115
	global_store_dwordx4 v[168:169], v[112:115], off offset:256
	global_load_dwordx4 v[112:115], v[166:167], off offset:256 nt
	v_ashrrev_i32_e32 v165, 31, v164
	v_lshlrev_b64 v[156:157], 12, v[164:165]
	v_or_b32_e32 v124, 32, v146
	v_lshl_add_u64 v[156:157], s[2:3], 0, v[156:157]
	v_mad_i64_i32 v[126:127], s[0:1], v124, s38, v[148:149]
	v_lshl_add_u64 v[156:157], v[156:157], 0, v[144:145]
	v_lshl_add_u64 v[126:127], v[126:127], 0, v[144:145]
	v_ashrrev_i32_e32 v125, 31, v124
	s_waitcnt vmcnt(2)
	v_lshlrev_b32_e32 v116, 16, v120
	v_and_b32_e32 v117, 0xffff0000, v120
	v_lshlrev_b32_e32 v118, 16, v121
	v_and_b32_e32 v119, 0xffff0000, v121
	v_lshlrev_b32_e32 v120, 16, v122
	v_and_b32_e32 v121, 0xffff0000, v122
	v_lshlrev_b32_e32 v122, 16, v123
	v_and_b32_e32 v123, 0xffff0000, v123
	v_mul_f32_e32 v123, 0xbfb8aa3b, v123
	v_mul_f32_e32 v116, 0xbfb8aa3b, v116
	v_mul_f32_e32 v117, 0xbfb8aa3b, v117
	v_mul_f32_e32 v118, 0xbfb8aa3b, v118
	v_mul_f32_e32 v119, 0xbfb8aa3b, v119
	v_mul_f32_e32 v120, 0xbfb8aa3b, v120
	v_mul_f32_e32 v121, 0xbfb8aa3b, v121
	v_mul_f32_e32 v122, 0xbfb8aa3b, v122
	v_exp_f32_e32 v123, v123
	v_exp_f32_e32 v116, v116
	v_exp_f32_e32 v117, v117
	v_exp_f32_e32 v118, v118
	v_exp_f32_e32 v119, v119
	v_exp_f32_e32 v120, v120
	v_exp_f32_e32 v121, v121
	v_exp_f32_e32 v122, v122
	v_add_f32_e32 v123, 1.0, v123
	v_add_f32_e32 v116, 1.0, v116
	v_add_f32_e32 v117, 1.0, v117
	v_add_f32_e32 v118, 1.0, v118
	v_add_f32_e32 v119, 1.0, v119
	v_add_f32_e32 v120, 1.0, v120
	v_add_f32_e32 v121, 1.0, v121
	v_add_f32_e32 v122, 1.0, v122
	v_rcp_f32_e32 v123, v123
	v_rcp_f32_e32 v116, v116
	v_rcp_f32_e32 v117, v117
	v_rcp_f32_e32 v118, v118
	v_rcp_f32_e32 v119, v119
	v_rcp_f32_e32 v120, v120
	v_rcp_f32_e32 v121, v121
	v_rcp_f32_e32 v122, v122
	v_mul_f32_e32 v107, v107, v123
	v_mul_f32_e32 v108, v108, v116
	v_mul_f32_e32 v109, v109, v117
	v_mul_f32_e32 v110, v110, v118
	v_mul_f32_e32 v111, v111, v119
	v_mul_f32_e32 v116, v104, v120
	v_mul_f32_e32 v117, v105, v121
	v_mul_f32_e32 v118, v106, v122
	v_cvt_pk_bf16_f32 v104, v108, v109
	v_cvt_pk_bf16_f32 v105, v110, v111
	v_cvt_pk_bf16_f32 v106, v116, v117
	v_cvt_pk_bf16_f32 v107, v118, v107
	global_store_dwordx4 v[156:157], v[104:107], off
	global_load_dwordx4 v[104:107], v[126:127], off nt
	s_waitcnt vmcnt(2)
	v_lshlrev_b32_e32 v117, 16, v115
	v_and_b32_e32 v115, 0xffff0000, v115
	v_lshlrev_b32_e32 v110, 16, v112
	v_and_b32_e32 v111, 0xffff0000, v112
	v_lshlrev_b32_e32 v112, 16, v113
	v_and_b32_e32 v113, 0xffff0000, v113
	v_lshlrev_b32_e32 v116, 16, v114
	v_and_b32_e32 v114, 0xffff0000, v114
	v_mul_f32_e32 v115, 0xbfb8aa3b, v115
	v_mul_f32_e32 v110, 0xbfb8aa3b, v110
	v_mul_f32_e32 v111, 0xbfb8aa3b, v111
	v_mul_f32_e32 v112, 0xbfb8aa3b, v112
	v_mul_f32_e32 v113, 0xbfb8aa3b, v113
	v_mul_f32_e32 v116, 0xbfb8aa3b, v116
	v_mul_f32_e32 v114, 0xbfb8aa3b, v114
	v_mul_f32_e32 v117, 0xbfb8aa3b, v117
	v_exp_f32_e32 v115, v115
	v_exp_f32_e32 v110, v110
	v_exp_f32_e32 v111, v111
	v_exp_f32_e32 v112, v112
	v_exp_f32_e32 v113, v113
	v_exp_f32_e32 v116, v116
	v_exp_f32_e32 v114, v114
	v_exp_f32_e32 v117, v117
	v_add_f32_e32 v115, 1.0, v115
	v_add_f32_e32 v110, 1.0, v110
	v_add_f32_e32 v111, 1.0, v111
	v_add_f32_e32 v112, 1.0, v112
	v_add_f32_e32 v113, 1.0, v113
	v_add_f32_e32 v116, 1.0, v116
	v_add_f32_e32 v114, 1.0, v114
	v_add_f32_e32 v117, 1.0, v117
	v_rcp_f32_e32 v115, v115
	v_rcp_f32_e32 v110, v110
	v_rcp_f32_e32 v111, v111
	v_rcp_f32_e32 v112, v112
	v_rcp_f32_e32 v113, v113
	v_rcp_f32_e32 v116, v116
	v_rcp_f32_e32 v114, v114
	v_rcp_f32_e32 v117, v117
	v_mul_f32_e32 v99, v99, v115
	v_mul_f32_e32 v100, v100, v110
	v_mul_f32_e32 v101, v101, v111
	v_mul_f32_e32 v102, v102, v112
	v_mul_f32_e32 v103, v103, v113
	v_mul_f32_e32 v110, v96, v116
	v_mul_f32_e32 v111, v97, v114
	v_mul_f32_e32 v112, v98, v117
	v_cvt_pk_bf16_f32 v96, v100, v101
	v_cvt_pk_bf16_f32 v97, v102, v103
	v_cvt_pk_bf16_f32 v98, v110, v111
	v_cvt_pk_bf16_f32 v99, v112, v99
	global_store_dwordx4 v[156:157], v[96:99], off offset:256
	global_load_dwordx4 v[96:99], v[126:127], off offset:256 nt
	v_lshlrev_b64 v[108:109], 12, v[124:125]
	s_waitcnt vmcnt(2)
	v_lshlrev_b32_e32 v100, 16, v104
	v_and_b32_e32 v101, 0xffff0000, v104
	v_mul_f32_e32 v100, 0xbfb8aa3b, v100
	v_mul_f32_e32 v101, 0xbfb8aa3b, v101
	v_exp_f32_e32 v100, v100
	v_exp_f32_e32 v101, v101
	v_lshlrev_b32_e32 v102, 16, v105
	v_and_b32_e32 v103, 0xffff0000, v105
	v_lshlrev_b32_e32 v104, 16, v106
	v_and_b32_e32 v105, 0xffff0000, v106
	v_lshlrev_b32_e32 v106, 16, v107
	v_and_b32_e32 v107, 0xffff0000, v107
	v_mul_f32_e32 v102, 0xbfb8aa3b, v102
	v_mul_f32_e32 v103, 0xbfb8aa3b, v103
	v_mul_f32_e32 v104, 0xbfb8aa3b, v104
	v_mul_f32_e32 v105, 0xbfb8aa3b, v105
	v_mul_f32_e32 v106, 0xbfb8aa3b, v106
	v_mul_f32_e32 v107, 0xbfb8aa3b, v107
	v_exp_f32_e32 v102, v102
	v_exp_f32_e32 v103, v103
	v_exp_f32_e32 v104, v104
	v_exp_f32_e32 v105, v105
	v_add_f32_e32 v100, 1.0, v100
	v_add_f32_e32 v101, 1.0, v101
	v_exp_f32_e32 v106, v106
	v_exp_f32_e32 v107, v107
	v_rcp_f32_e32 v100, v100
	v_rcp_f32_e32 v101, v101
	v_add_f32_e32 v102, 1.0, v102
	v_add_f32_e32 v103, 1.0, v103
	v_add_f32_e32 v104, 1.0, v104
	v_add_f32_e32 v105, 1.0, v105
	v_rcp_f32_e32 v102, v102
	v_rcp_f32_e32 v103, v103
	v_rcp_f32_e32 v104, v104
	v_rcp_f32_e32 v105, v105
	v_mul_f32_e32 v100, v92, v100
	v_mul_f32_e32 v101, v93, v101
	v_add_f32_e32 v92, 1.0, v106
	v_add_f32_e32 v93, 1.0, v107
	v_rcp_f32_e32 v92, v92
	v_rcp_f32_e32 v93, v93
	v_mul_f32_e32 v94, v94, v102
	v_mul_f32_e32 v95, v95, v103
	v_mul_f32_e32 v102, v88, v104
	v_mul_f32_e32 v103, v89, v105
	v_lshl_add_u64 v[88:89], s[2:3], 0, v[108:109]
	v_mul_f32_e32 v104, v90, v92
	v_mul_f32_e32 v91, v91, v93
	v_lshl_add_u64 v[92:93], v[88:89], 0, v[144:145]
	v_cvt_pk_bf16_f32 v88, v100, v101
	v_cvt_pk_bf16_f32 v89, v94, v95
	v_or_b32_e32 v94, 48, v146
	v_cvt_pk_bf16_f32 v90, v102, v103
	v_cvt_pk_bf16_f32 v91, v104, v91
	global_store_dwordx4 v[92:93], v[88:91], off
	s_waitcnt vmcnt(1)
	v_lshlrev_b32_e32 v104, 16, v99
	v_and_b32_e32 v99, 0xffff0000, v99
	v_mad_i64_i32 v[88:89], s[0:1], v94, s38, v[148:149]
	v_lshl_add_u64 v[100:101], v[88:89], 0, v[144:145]
	global_load_dwordx4 v[88:91], v[100:101], off nt
	v_lshlrev_b32_e32 v95, 16, v96
	v_and_b32_e32 v96, 0xffff0000, v96
	v_lshlrev_b32_e32 v102, 16, v97
	v_and_b32_e32 v97, 0xffff0000, v97
	v_lshlrev_b32_e32 v103, 16, v98
	v_and_b32_e32 v98, 0xffff0000, v98
	v_mul_f32_e32 v99, 0xbfb8aa3b, v99
	v_mul_f32_e32 v95, 0xbfb8aa3b, v95
	v_mul_f32_e32 v96, 0xbfb8aa3b, v96
	v_mul_f32_e32 v102, 0xbfb8aa3b, v102
	v_mul_f32_e32 v97, 0xbfb8aa3b, v97
	v_mul_f32_e32 v103, 0xbfb8aa3b, v103
	v_mul_f32_e32 v98, 0xbfb8aa3b, v98
	v_mul_f32_e32 v104, 0xbfb8aa3b, v104
	v_exp_f32_e32 v99, v99
	v_exp_f32_e32 v95, v95
	v_exp_f32_e32 v96, v96
	v_exp_f32_e32 v102, v102
	v_exp_f32_e32 v97, v97
	v_exp_f32_e32 v103, v103
	v_exp_f32_e32 v98, v98
	v_exp_f32_e32 v104, v104
	v_add_f32_e32 v99, 1.0, v99
	v_add_f32_e32 v95, 1.0, v95
	v_add_f32_e32 v96, 1.0, v96
	v_add_f32_e32 v102, 1.0, v102
	v_add_f32_e32 v97, 1.0, v97
	v_add_f32_e32 v103, 1.0, v103
	v_add_f32_e32 v98, 1.0, v98
	v_add_f32_e32 v104, 1.0, v104
	v_rcp_f32_e32 v99, v99
	v_rcp_f32_e32 v95, v95
	v_rcp_f32_e32 v96, v96
	v_rcp_f32_e32 v102, v102
	v_rcp_f32_e32 v97, v97
	v_rcp_f32_e32 v103, v103
	v_rcp_f32_e32 v98, v98
	v_rcp_f32_e32 v104, v104
	v_mul_f32_e32 v83, v83, v99
	v_mul_f32_e32 v84, v84, v95
	v_mul_f32_e32 v85, v85, v96
	v_mul_f32_e32 v86, v86, v102
	v_mul_f32_e32 v87, v87, v97
	v_mul_f32_e32 v95, v80, v103
	v_mul_f32_e32 v96, v81, v98
	v_mul_f32_e32 v97, v82, v104
	v_cvt_pk_bf16_f32 v80, v84, v85
	v_cvt_pk_bf16_f32 v81, v86, v87
	v_cvt_pk_bf16_f32 v82, v95, v96
	v_cvt_pk_bf16_f32 v83, v97, v83
	global_store_dwordx4 v[92:93], v[80:83], off offset:256
	global_load_dwordx4 v[80:83], v[100:101], off offset:256 nt
	v_ashrrev_i32_e32 v95, 31, v94
	s_waitcnt vmcnt(2)
	v_and_b32_e32 v85, 0xffff0000, v88
	v_lshlrev_b32_e32 v86, 16, v89
	v_lshlrev_b32_e32 v84, 16, v88
	v_mul_f32_e32 v85, 0xbfb8aa3b, v85
	v_mul_f32_e32 v86, 0xbfb8aa3b, v86
	v_mul_f32_e32 v84, 0xbfb8aa3b, v84
	v_exp_f32_e32 v88, v85
	v_exp_f32_e32 v86, v86
	v_exp_f32_e32 v87, v84
	v_and_b32_e32 v89, 0xffff0000, v89
	v_add_f32_e32 v88, 1.0, v88
	v_add_f32_e32 v86, 1.0, v86
	v_add_f32_e32 v87, 1.0, v87
	v_rcp_f32_e32 v88, v88
	v_rcp_f32_e32 v86, v86
	v_mul_f32_e32 v89, 0xbfb8aa3b, v89
	v_rcp_f32_e32 v87, v87
	v_exp_f32_e32 v89, v89
	v_mul_f32_e32 v88, v77, v88
	v_mul_f32_e32 v78, v78, v86
	v_lshlrev_b32_e32 v77, 16, v90
	v_and_b32_e32 v86, 0xffff0000, v90
	v_mul_f32_e32 v87, v76, v87
	v_add_f32_e32 v76, 1.0, v89
	v_mul_f32_e32 v77, 0xbfb8aa3b, v77
	v_mul_f32_e32 v86, 0xbfb8aa3b, v86
	v_rcp_f32_e32 v76, v76
	v_exp_f32_e32 v77, v77
	v_exp_f32_e32 v86, v86
	v_and_b32_e32 v89, 0xffff0000, v91
	v_mul_f32_e32 v79, v79, v76
	v_add_f32_e32 v76, 1.0, v77
	v_add_f32_e32 v77, 1.0, v86
	v_lshlrev_b32_e32 v86, 16, v91
	v_mul_f32_e32 v89, 0xbfb8aa3b, v89
	v_mul_f32_e32 v86, 0xbfb8aa3b, v86
	v_exp_f32_e32 v89, v89
	v_exp_f32_e32 v86, v86
	v_rcp_f32_e32 v76, v76
	v_rcp_f32_e32 v77, v77
	v_add_f32_e32 v89, 1.0, v89
	v_add_f32_e32 v86, 1.0, v86
	v_rcp_f32_e32 v89, v89
	v_rcp_f32_e32 v86, v86
	v_lshlrev_b64 v[84:85], 12, v[94:95]
	v_mul_f32_e32 v90, v72, v76
	v_mul_f32_e32 v91, v73, v77
	v_lshl_add_u64 v[72:73], s[2:3], 0, v[84:85]
	v_mul_f32_e32 v75, v75, v89
	v_lshl_add_u64 v[76:77], v[72:73], 0, v[144:145]
	v_cvt_pk_bf16_f32 v72, v87, v88
	v_cvt_pk_bf16_f32 v73, v78, v79
	v_add_u32_e32 v78, 0x80, v146
	v_mul_f32_e32 v86, v74, v86
	v_cvt_pk_bf16_f32 v74, v90, v91
	v_cvt_pk_bf16_f32 v75, v86, v75
	global_store_dwordx4 v[76:77], v[72:75], off
	s_waitcnt vmcnt(1)
	v_lshlrev_b32_e32 v79, 16, v80
	v_and_b32_e32 v80, 0xffff0000, v80
	v_mad_i64_i32 v[72:73], s[0:1], v78, s38, v[148:149]
	v_lshl_add_u64 v[84:85], v[72:73], 0, v[144:145]
	global_load_dwordx4 v[72:75], v[84:85], off nt
	v_mul_f32_e32 v79, 0xbfb8aa3b, v79
	v_mul_f32_e32 v80, 0xbfb8aa3b, v80
	v_exp_f32_e32 v79, v79
	v_exp_f32_e32 v80, v80
	v_lshlrev_b32_e32 v86, 16, v81
	v_and_b32_e32 v81, 0xffff0000, v81
	v_add_f32_e32 v79, 1.0, v79
	v_add_f32_e32 v80, 1.0, v80
	v_mul_f32_e32 v81, 0xbfb8aa3b, v81
	v_rcp_f32_e32 v79, v79
	v_rcp_f32_e32 v80, v80
	v_exp_f32_e32 v81, v81
	v_mul_f32_e32 v86, 0xbfb8aa3b, v86
	v_mul_f32_e32 v68, v68, v79
	v_mul_f32_e32 v69, v69, v80
	v_add_f32_e32 v79, 1.0, v81
	v_lshlrev_b32_e32 v80, 16, v82
	v_and_b32_e32 v81, 0xffff0000, v82
	v_mul_f32_e32 v80, 0xbfb8aa3b, v80
	v_mul_f32_e32 v81, 0xbfb8aa3b, v81
	v_rcp_f32_e32 v79, v79
	v_exp_f32_e32 v80, v80
	v_exp_f32_e32 v81, v81
	v_and_b32_e32 v82, 0xffff0000, v83
	v_mul_f32_e32 v71, v71, v79
	v_add_f32_e32 v79, 1.0, v80
	v_add_f32_e32 v80, 1.0, v81
	v_lshlrev_b32_e32 v81, 16, v83
	v_mul_f32_e32 v82, 0xbfb8aa3b, v82
	v_mul_f32_e32 v81, 0xbfb8aa3b, v81
	v_exp_f32_e32 v82, v82
	v_exp_f32_e32 v86, v86
	v_exp_f32_e32 v81, v81
	v_rcp_f32_e32 v79, v79
	v_add_f32_e32 v82, 1.0, v82
	v_add_f32_e32 v86, 1.0, v86
	v_add_f32_e32 v81, 1.0, v81
	v_rcp_f32_e32 v82, v82
	v_rcp_f32_e32 v86, v86
	v_rcp_f32_e32 v80, v80
	v_rcp_f32_e32 v81, v81
	v_mul_f32_e32 v67, v67, v82
	v_mul_f32_e32 v70, v70, v86
	v_mul_f32_e32 v79, v64, v79
	v_mul_f32_e32 v80, v65, v80
	v_mul_f32_e32 v81, v66, v81
	v_cvt_pk_bf16_f32 v64, v68, v69
	v_cvt_pk_bf16_f32 v65, v70, v71
	v_cvt_pk_bf16_f32 v66, v79, v80
	v_cvt_pk_bf16_f32 v67, v81, v67
	global_store_dwordx4 v[76:77], v[64:67], off offset:256
	global_load_dwordx4 v[64:67], v[84:85], off offset:256 nt
	v_ashrrev_i32_e32 v79, 31, v78
	s_waitcnt vmcnt(2)
	v_lshlrev_b32_e32 v68, 16, v72
	v_and_b32_e32 v71, 0xffff0000, v72
	v_lshlrev_b32_e32 v72, 16, v73
	v_mul_f32_e32 v71, 0xbfb8aa3b, v71
	v_mul_f32_e32 v72, 0xbfb8aa3b, v72
	v_mul_f32_e32 v68, 0xbfb8aa3b, v68
	v_exp_f32_e32 v71, v71
	v_exp_f32_e32 v72, v72
	v_exp_f32_e32 v70, v68
	v_and_b32_e32 v73, 0xffff0000, v73
	v_add_f32_e32 v71, 1.0, v71
	v_add_f32_e32 v72, 1.0, v72
	v_add_f32_e32 v70, 1.0, v70
	v_rcp_f32_e32 v71, v71
	v_rcp_f32_e32 v72, v72
	v_mul_f32_e32 v73, 0xbfb8aa3b, v73
	v_rcp_f32_e32 v70, v70
	v_exp_f32_e32 v73, v73
	v_mul_f32_e32 v71, v61, v71
	v_mul_f32_e32 v62, v62, v72
	v_lshlrev_b32_e32 v61, 16, v74
	v_and_b32_e32 v72, 0xffff0000, v74
	v_mul_f32_e32 v70, v60, v70
	v_add_f32_e32 v60, 1.0, v73
	v_mul_f32_e32 v61, 0xbfb8aa3b, v61
	v_mul_f32_e32 v72, 0xbfb8aa3b, v72
	v_rcp_f32_e32 v60, v60
	v_exp_f32_e32 v61, v61
	v_exp_f32_e32 v72, v72
	v_and_b32_e32 v73, 0xffff0000, v75
	v_mul_f32_e32 v63, v63, v60
	v_add_f32_e32 v60, 1.0, v61
	v_add_f32_e32 v61, 1.0, v72
	v_lshlrev_b32_e32 v72, 16, v75
	v_mul_f32_e32 v73, 0xbfb8aa3b, v73
	v_mul_f32_e32 v72, 0xbfb8aa3b, v72
	v_exp_f32_e32 v73, v73
	v_exp_f32_e32 v72, v72
	v_rcp_f32_e32 v60, v60
	v_rcp_f32_e32 v61, v61
	v_add_f32_e32 v73, 1.0, v73
	v_add_f32_e32 v72, 1.0, v72
	v_rcp_f32_e32 v73, v73
	v_rcp_f32_e32 v72, v72
	v_lshlrev_b64 v[68:69], 12, v[78:79]
	v_mul_f32_e32 v74, v56, v60
	v_mul_f32_e32 v75, v57, v61
	v_lshl_add_u64 v[56:57], s[2:3], 0, v[68:69]
	v_mul_f32_e32 v59, v59, v73
	v_lshl_add_u64 v[60:61], v[56:57], 0, v[144:145]
	v_cvt_pk_bf16_f32 v56, v70, v71
	v_cvt_pk_bf16_f32 v57, v62, v63
	v_add_u32_e32 v62, 0x90, v146
	v_mul_f32_e32 v72, v58, v72
	v_cvt_pk_bf16_f32 v58, v74, v75
	v_cvt_pk_bf16_f32 v59, v72, v59
	global_store_dwordx4 v[60:61], v[56:59], off
	s_waitcnt vmcnt(1)
	v_lshlrev_b32_e32 v63, 16, v64
	v_and_b32_e32 v64, 0xffff0000, v64
	v_mad_i64_i32 v[56:57], s[0:1], v62, s38, v[148:149]
	v_lshl_add_u64 v[68:69], v[56:57], 0, v[144:145]
	global_load_dwordx4 v[56:59], v[68:69], off nt
	v_mul_f32_e32 v63, 0xbfb8aa3b, v63
	v_mul_f32_e32 v64, 0xbfb8aa3b, v64
	v_exp_f32_e32 v63, v63
	v_exp_f32_e32 v64, v64
	v_lshlrev_b32_e32 v70, 16, v65
	v_and_b32_e32 v65, 0xffff0000, v65
	v_add_f32_e32 v63, 1.0, v63
	v_add_f32_e32 v64, 1.0, v64
	v_mul_f32_e32 v65, 0xbfb8aa3b, v65
	v_rcp_f32_e32 v63, v63
	v_rcp_f32_e32 v64, v64
	v_exp_f32_e32 v65, v65
	v_mul_f32_e32 v70, 0xbfb8aa3b, v70
	v_mul_f32_e32 v52, v52, v63
	v_mul_f32_e32 v53, v53, v64
	v_add_f32_e32 v63, 1.0, v65
	v_lshlrev_b32_e32 v64, 16, v66
	v_and_b32_e32 v65, 0xffff0000, v66
	v_mul_f32_e32 v64, 0xbfb8aa3b, v64
	v_mul_f32_e32 v65, 0xbfb8aa3b, v65
	v_rcp_f32_e32 v63, v63
	v_exp_f32_e32 v64, v64
	v_exp_f32_e32 v65, v65
	v_and_b32_e32 v66, 0xffff0000, v67
	v_mul_f32_e32 v55, v55, v63
	v_add_f32_e32 v63, 1.0, v64
	v_add_f32_e32 v64, 1.0, v65
	v_lshlrev_b32_e32 v65, 16, v67
	v_mul_f32_e32 v66, 0xbfb8aa3b, v66
	v_mul_f32_e32 v65, 0xbfb8aa3b, v65
	v_exp_f32_e32 v66, v66
	v_exp_f32_e32 v70, v70
	v_exp_f32_e32 v65, v65
	v_rcp_f32_e32 v63, v63
	v_add_f32_e32 v66, 1.0, v66
	v_add_f32_e32 v70, 1.0, v70
	v_add_f32_e32 v65, 1.0, v65
	v_rcp_f32_e32 v66, v66
	v_rcp_f32_e32 v70, v70
	v_rcp_f32_e32 v64, v64
	v_rcp_f32_e32 v65, v65
	v_mul_f32_e32 v51, v51, v66
	v_mul_f32_e32 v54, v54, v70
	v_mul_f32_e32 v63, v48, v63
	v_mul_f32_e32 v64, v49, v64
	v_mul_f32_e32 v65, v50, v65
	v_cvt_pk_bf16_f32 v48, v52, v53
	v_cvt_pk_bf16_f32 v49, v54, v55
	v_cvt_pk_bf16_f32 v50, v63, v64
	v_cvt_pk_bf16_f32 v51, v65, v51
	global_store_dwordx4 v[60:61], v[48:51], off offset:256
	global_load_dwordx4 v[48:51], v[68:69], off offset:256 nt
	v_ashrrev_i32_e32 v63, 31, v62
	s_waitcnt vmcnt(2)
	v_lshlrev_b32_e32 v52, 16, v56
	v_and_b32_e32 v55, 0xffff0000, v56
	v_lshlrev_b32_e32 v56, 16, v57
	v_mul_f32_e32 v55, 0xbfb8aa3b, v55
	v_mul_f32_e32 v56, 0xbfb8aa3b, v56
	v_mul_f32_e32 v52, 0xbfb8aa3b, v52
	v_exp_f32_e32 v55, v55
	v_exp_f32_e32 v56, v56
	v_exp_f32_e32 v54, v52
	v_and_b32_e32 v57, 0xffff0000, v57
	v_add_f32_e32 v55, 1.0, v55
	v_add_f32_e32 v56, 1.0, v56
	v_add_f32_e32 v54, 1.0, v54
	v_rcp_f32_e32 v55, v55
	v_rcp_f32_e32 v56, v56
	v_mul_f32_e32 v57, 0xbfb8aa3b, v57
	v_rcp_f32_e32 v54, v54
	v_exp_f32_e32 v57, v57
	v_mul_f32_e32 v55, v45, v55
	v_mul_f32_e32 v46, v46, v56
	v_lshlrev_b32_e32 v45, 16, v58
	v_and_b32_e32 v56, 0xffff0000, v58
	v_mul_f32_e32 v54, v44, v54
	v_add_f32_e32 v44, 1.0, v57
	v_mul_f32_e32 v45, 0xbfb8aa3b, v45
	v_mul_f32_e32 v56, 0xbfb8aa3b, v56
	v_rcp_f32_e32 v44, v44
	v_exp_f32_e32 v45, v45
	v_exp_f32_e32 v56, v56
	v_and_b32_e32 v57, 0xffff0000, v59
	v_mul_f32_e32 v47, v47, v44
	v_add_f32_e32 v44, 1.0, v45
	v_add_f32_e32 v45, 1.0, v56
	v_lshlrev_b32_e32 v56, 16, v59
	v_mul_f32_e32 v57, 0xbfb8aa3b, v57
	v_mul_f32_e32 v56, 0xbfb8aa3b, v56
	v_exp_f32_e32 v57, v57
	v_exp_f32_e32 v56, v56
	v_rcp_f32_e32 v44, v44
	v_rcp_f32_e32 v45, v45
	v_add_f32_e32 v57, 1.0, v57
	v_add_f32_e32 v56, 1.0, v56
	v_rcp_f32_e32 v57, v57
	v_rcp_f32_e32 v56, v56
	v_lshlrev_b64 v[52:53], 12, v[62:63]
	v_mul_f32_e32 v58, v40, v44
	v_mul_f32_e32 v59, v41, v45
	v_lshl_add_u64 v[40:41], s[2:3], 0, v[52:53]
	v_mul_f32_e32 v43, v43, v57
	v_lshl_add_u64 v[44:45], v[40:41], 0, v[144:145]
	v_cvt_pk_bf16_f32 v40, v54, v55
	v_cvt_pk_bf16_f32 v41, v46, v47
	v_add_u32_e32 v46, 0xa0, v146
	v_mul_f32_e32 v56, v42, v56
	v_cvt_pk_bf16_f32 v42, v58, v59
	v_cvt_pk_bf16_f32 v43, v56, v43
	global_store_dwordx4 v[44:45], v[40:43], off
	s_waitcnt vmcnt(1)
	v_lshlrev_b32_e32 v47, 16, v48
	v_and_b32_e32 v48, 0xffff0000, v48
	v_mad_i64_i32 v[40:41], s[0:1], v46, s38, v[148:149]
	v_lshl_add_u64 v[52:53], v[40:41], 0, v[144:145]
	global_load_dwordx4 v[40:43], v[52:53], off nt
	v_mul_f32_e32 v47, 0xbfb8aa3b, v47
	v_mul_f32_e32 v48, 0xbfb8aa3b, v48
	v_exp_f32_e32 v47, v47
	v_exp_f32_e32 v48, v48
	v_lshlrev_b32_e32 v54, 16, v49
	v_and_b32_e32 v49, 0xffff0000, v49
	v_add_f32_e32 v47, 1.0, v47
	v_add_f32_e32 v48, 1.0, v48
	v_mul_f32_e32 v49, 0xbfb8aa3b, v49
	v_rcp_f32_e32 v47, v47
	v_rcp_f32_e32 v48, v48
	v_exp_f32_e32 v49, v49
	v_mul_f32_e32 v54, 0xbfb8aa3b, v54
	v_mul_f32_e32 v36, v36, v47
	v_mul_f32_e32 v37, v37, v48
	v_add_f32_e32 v47, 1.0, v49
	v_lshlrev_b32_e32 v48, 16, v50
	v_and_b32_e32 v49, 0xffff0000, v50
	v_mul_f32_e32 v48, 0xbfb8aa3b, v48
	v_mul_f32_e32 v49, 0xbfb8aa3b, v49
	v_rcp_f32_e32 v47, v47
	v_exp_f32_e32 v48, v48
	v_exp_f32_e32 v49, v49
	v_and_b32_e32 v50, 0xffff0000, v51
	v_mul_f32_e32 v39, v39, v47
	v_add_f32_e32 v47, 1.0, v48
	v_add_f32_e32 v48, 1.0, v49
	v_lshlrev_b32_e32 v49, 16, v51
	v_mul_f32_e32 v50, 0xbfb8aa3b, v50
	v_mul_f32_e32 v49, 0xbfb8aa3b, v49
	v_exp_f32_e32 v50, v50
	v_exp_f32_e32 v54, v54
	v_exp_f32_e32 v49, v49
	v_rcp_f32_e32 v47, v47
	v_add_f32_e32 v50, 1.0, v50
	v_add_f32_e32 v54, 1.0, v54
	v_add_f32_e32 v49, 1.0, v49
	v_rcp_f32_e32 v50, v50
	v_rcp_f32_e32 v54, v54
	v_rcp_f32_e32 v48, v48
	v_rcp_f32_e32 v49, v49
	v_mul_f32_e32 v35, v35, v50
	v_mul_f32_e32 v38, v38, v54
	v_mul_f32_e32 v47, v32, v47
	v_mul_f32_e32 v48, v33, v48
	v_mul_f32_e32 v49, v34, v49
	v_cvt_pk_bf16_f32 v32, v36, v37
	v_cvt_pk_bf16_f32 v33, v38, v39
	v_cvt_pk_bf16_f32 v34, v47, v48
	v_cvt_pk_bf16_f32 v35, v49, v35
	global_store_dwordx4 v[44:45], v[32:35], off offset:256
	global_load_dwordx4 v[32:35], v[52:53], off offset:256 nt
	v_ashrrev_i32_e32 v47, 31, v46
	s_waitcnt vmcnt(2)
	v_lshlrev_b32_e32 v36, 16, v40
	v_and_b32_e32 v39, 0xffff0000, v40
	v_lshlrev_b32_e32 v40, 16, v41
	v_mul_f32_e32 v39, 0xbfb8aa3b, v39
	v_mul_f32_e32 v40, 0xbfb8aa3b, v40
	v_mul_f32_e32 v36, 0xbfb8aa3b, v36
	v_exp_f32_e32 v39, v39
	v_exp_f32_e32 v40, v40
	v_exp_f32_e32 v38, v36
	v_and_b32_e32 v41, 0xffff0000, v41
	v_add_f32_e32 v39, 1.0, v39
	v_add_f32_e32 v40, 1.0, v40
	v_add_f32_e32 v38, 1.0, v38
	v_rcp_f32_e32 v39, v39
	v_rcp_f32_e32 v40, v40
	v_mul_f32_e32 v41, 0xbfb8aa3b, v41
	v_rcp_f32_e32 v38, v38
	v_exp_f32_e32 v41, v41
	v_mul_f32_e32 v39, v29, v39
	v_mul_f32_e32 v30, v30, v40
	v_lshlrev_b32_e32 v29, 16, v42
	v_and_b32_e32 v40, 0xffff0000, v42
	v_mul_f32_e32 v38, v28, v38
	v_add_f32_e32 v28, 1.0, v41
	v_mul_f32_e32 v29, 0xbfb8aa3b, v29
	v_mul_f32_e32 v40, 0xbfb8aa3b, v40
	v_rcp_f32_e32 v28, v28
	v_exp_f32_e32 v29, v29
	v_exp_f32_e32 v40, v40
	v_and_b32_e32 v41, 0xffff0000, v43
	v_mul_f32_e32 v31, v31, v28
	v_add_f32_e32 v28, 1.0, v29
	v_add_f32_e32 v29, 1.0, v40
	v_lshlrev_b32_e32 v40, 16, v43
	v_mul_f32_e32 v41, 0xbfb8aa3b, v41
	v_mul_f32_e32 v40, 0xbfb8aa3b, v40
	v_exp_f32_e32 v41, v41
	v_exp_f32_e32 v40, v40
	v_rcp_f32_e32 v28, v28
	v_rcp_f32_e32 v29, v29
	v_add_f32_e32 v41, 1.0, v41
	v_add_f32_e32 v40, 1.0, v40
	v_rcp_f32_e32 v41, v41
	v_rcp_f32_e32 v40, v40
	v_lshlrev_b64 v[36:37], 12, v[46:47]
	v_mul_f32_e32 v42, v24, v28
	v_mul_f32_e32 v43, v25, v29
	v_lshl_add_u64 v[24:25], s[2:3], 0, v[36:37]
	v_mul_f32_e32 v27, v27, v41
	v_lshl_add_u64 v[28:29], v[24:25], 0, v[144:145]
	v_cvt_pk_bf16_f32 v24, v38, v39
	v_mul_f32_e32 v40, v26, v40
	v_cvt_pk_bf16_f32 v25, v30, v31
	v_cvt_pk_bf16_f32 v26, v42, v43
	v_cvt_pk_bf16_f32 v27, v40, v27
	global_store_dwordx4 v[28:29], v[24:27], off
	v_add_u32_e32 v30, 0xb0, v146
	s_waitcnt vmcnt(1)
	v_lshlrev_b32_e32 v38, 16, v33
	v_lshlrev_b32_e32 v24, 16, v32
	v_mul_f32_e32 v31, 0xbfb8aa3b, v24
	v_mad_i64_i32 v[24:25], s[0:1], v30, s38, v[148:149]
	v_lshl_add_u64 v[36:37], v[24:25], 0, v[144:145]
	v_and_b32_e32 v32, 0xffff0000, v32
	global_load_dwordx4 v[24:27], v[36:37], off nt
	v_mul_f32_e32 v32, 0xbfb8aa3b, v32
	v_exp_f32_e32 v31, v31
	v_exp_f32_e32 v32, v32
	v_and_b32_e32 v33, 0xffff0000, v33
	v_mul_f32_e32 v33, 0xbfb8aa3b, v33
	v_add_f32_e32 v31, 1.0, v31
	v_add_f32_e32 v32, 1.0, v32
	v_rcp_f32_e32 v31, v31
	v_rcp_f32_e32 v32, v32
	v_exp_f32_e32 v33, v33
	v_mul_f32_e32 v38, 0xbfb8aa3b, v38
	v_mul_f32_e32 v20, v20, v31
	v_mul_f32_e32 v21, v21, v32
	v_add_f32_e32 v31, 1.0, v33
	v_lshlrev_b32_e32 v32, 16, v34
	v_and_b32_e32 v33, 0xffff0000, v34
	v_mul_f32_e32 v32, 0xbfb8aa3b, v32
	v_mul_f32_e32 v33, 0xbfb8aa3b, v33
	v_rcp_f32_e32 v31, v31
	v_exp_f32_e32 v32, v32
	v_exp_f32_e32 v33, v33
	v_and_b32_e32 v34, 0xffff0000, v35
	v_mul_f32_e32 v23, v23, v31
	v_add_f32_e32 v31, 1.0, v32
	v_add_f32_e32 v32, 1.0, v33
	v_lshlrev_b32_e32 v33, 16, v35
	v_mul_f32_e32 v34, 0xbfb8aa3b, v34
	v_mul_f32_e32 v33, 0xbfb8aa3b, v33
	v_exp_f32_e32 v34, v34
	v_exp_f32_e32 v38, v38
	v_exp_f32_e32 v33, v33
	v_rcp_f32_e32 v31, v31
	v_add_f32_e32 v34, 1.0, v34
	v_add_f32_e32 v38, 1.0, v38
	v_add_f32_e32 v33, 1.0, v33
	v_rcp_f32_e32 v34, v34
	v_rcp_f32_e32 v38, v38
	v_rcp_f32_e32 v32, v32
	v_rcp_f32_e32 v33, v33
	v_mul_f32_e32 v19, v19, v34
	v_mul_f32_e32 v22, v22, v38
	v_mul_f32_e32 v31, v16, v31
	v_mul_f32_e32 v32, v17, v32
	v_mul_f32_e32 v33, v18, v33
	v_cvt_pk_bf16_f32 v16, v20, v21
	v_cvt_pk_bf16_f32 v17, v22, v23
	v_cvt_pk_bf16_f32 v18, v31, v32
	v_cvt_pk_bf16_f32 v19, v33, v19
	global_store_dwordx4 v[28:29], v[16:19], off offset:256
	global_load_dwordx4 v[16:19], v[36:37], off offset:256 nt
	v_ashrrev_i32_e32 v31, 31, v30
	s_mov_b64 s[0:1], -1
	s_waitcnt vmcnt(2)
	v_lshlrev_b32_e32 v20, 16, v24
	v_and_b32_e32 v23, 0xffff0000, v24
	v_lshlrev_b32_e32 v24, 16, v25
	v_mul_f32_e32 v23, 0xbfb8aa3b, v23
	v_mul_f32_e32 v24, 0xbfb8aa3b, v24
	v_mul_f32_e32 v20, 0xbfb8aa3b, v20
	v_exp_f32_e32 v23, v23
	v_exp_f32_e32 v24, v24
	v_exp_f32_e32 v22, v20
	v_and_b32_e32 v25, 0xffff0000, v25
	v_add_f32_e32 v23, 1.0, v23
	v_add_f32_e32 v24, 1.0, v24
	v_add_f32_e32 v22, 1.0, v22
	v_rcp_f32_e32 v23, v23
	v_rcp_f32_e32 v24, v24
	v_mul_f32_e32 v25, 0xbfb8aa3b, v25
	v_rcp_f32_e32 v22, v22
	v_exp_f32_e32 v25, v25
	v_mul_f32_e32 v23, v13, v23
	v_mul_f32_e32 v14, v14, v24
	v_lshlrev_b32_e32 v13, 16, v26
	v_and_b32_e32 v24, 0xffff0000, v26
	v_mul_f32_e32 v22, v12, v22
	v_add_f32_e32 v12, 1.0, v25
	v_mul_f32_e32 v13, 0xbfb8aa3b, v13
	v_mul_f32_e32 v24, 0xbfb8aa3b, v24
	v_rcp_f32_e32 v12, v12
	v_exp_f32_e32 v13, v13
	v_exp_f32_e32 v24, v24
	v_and_b32_e32 v25, 0xffff0000, v27
	v_mul_f32_e32 v15, v15, v12
	v_add_f32_e32 v12, 1.0, v13
	v_add_f32_e32 v13, 1.0, v24
	v_lshlrev_b32_e32 v24, 16, v27
	v_mul_f32_e32 v24, 0xbfb8aa3b, v24
	v_exp_f32_e32 v24, v24
	v_mul_f32_e32 v25, 0xbfb8aa3b, v25
	v_exp_f32_e32 v25, v25
	v_rcp_f32_e32 v12, v12
	v_add_f32_e32 v24, 1.0, v24
	v_rcp_f32_e32 v24, v24
	v_rcp_f32_e32 v13, v13
	v_add_f32_e32 v25, 1.0, v25
	v_rcp_f32_e32 v25, v25
	v_lshlrev_b64 v[20:21], 12, v[30:31]
	v_mul_f32_e32 v24, v10, v24
	v_mul_f32_e32 v26, v8, v12
	v_mul_f32_e32 v27, v9, v13
	v_lshl_add_u64 v[8:9], s[2:3], 0, v[20:21]
	v_mul_f32_e32 v11, v11, v25
	s_waitcnt vmcnt(0)
	v_lshlrev_b32_e32 v10, 16, v16
	v_mul_f32_e32 v10, 0xbfb8aa3b, v10
	v_lshl_add_u64 v[12:13], v[8:9], 0, v[144:145]
	v_cvt_pk_bf16_f32 v9, v14, v15
	v_exp_f32_e32 v14, v10
	v_cvt_pk_bf16_f32 v10, v26, v27
	v_cvt_pk_bf16_f32 v8, v22, v23
	v_cvt_pk_bf16_f32 v11, v24, v11
	global_store_dwordx4 v[12:13], v[8:11], off
	s_nop 1
	v_and_b32_e32 v9, 0xffff0000, v16
	v_lshlrev_b32_e32 v10, 16, v17
	v_mul_f32_e32 v9, 0xbfb8aa3b, v9
	v_mul_f32_e32 v10, 0xbfb8aa3b, v10
	v_exp_f32_e32 v9, v9
	v_exp_f32_e32 v10, v10
	v_and_b32_e32 v11, 0xffff0000, v17
	v_add_f32_e32 v8, 1.0, v14
	v_add_f32_e32 v9, 1.0, v9
	v_add_f32_e32 v10, 1.0, v10
	v_rcp_f32_e32 v9, v9
	v_rcp_f32_e32 v10, v10
	v_mul_f32_e32 v11, 0xbfb8aa3b, v11
	v_rcp_f32_e32 v8, v8
	v_exp_f32_e32 v11, v11
	v_mul_f32_e32 v5, v5, v9
	v_mul_f32_e32 v6, v6, v10
	v_lshlrev_b32_e32 v9, 16, v18
	v_and_b32_e32 v10, 0xffff0000, v18
	v_mul_f32_e32 v4, v4, v8
	v_add_f32_e32 v8, 1.0, v11
	v_mul_f32_e32 v9, 0xbfb8aa3b, v9
	v_mul_f32_e32 v10, 0xbfb8aa3b, v10
	v_rcp_f32_e32 v8, v8
	v_exp_f32_e32 v9, v9
	v_exp_f32_e32 v10, v10
	v_and_b32_e32 v11, 0xffff0000, v19
	v_mul_f32_e32 v7, v7, v8
	v_add_f32_e32 v8, 1.0, v9
	v_add_f32_e32 v9, 1.0, v10
	v_lshlrev_b32_e32 v10, 16, v19
	v_mul_f32_e32 v11, 0xbfb8aa3b, v11
	v_mul_f32_e32 v10, 0xbfb8aa3b, v10
	v_exp_f32_e32 v11, v11
	v_exp_f32_e32 v10, v10
	v_rcp_f32_e32 v8, v8
	v_rcp_f32_e32 v9, v9
	v_add_f32_e32 v11, 1.0, v11
	v_add_f32_e32 v10, 1.0, v10
	v_rcp_f32_e32 v11, v11
	v_rcp_f32_e32 v10, v10
	v_mul_f32_e32 v8, v0, v8
	v_mul_f32_e32 v9, v1, v9
	v_mul_f32_e32 v3, v3, v11
	v_mul_f32_e32 v10, v2, v10
	v_cvt_pk_bf16_f32 v0, v4, v5
	v_cvt_pk_bf16_f32 v1, v6, v7
	v_cvt_pk_bf16_f32 v2, v8, v9
	v_cvt_pk_bf16_f32 v3, v10, v3
	global_store_dwordx4 v[12:13], v[0:3], off offset:256
	s_cbranch_vccnz .LBB0_832
	s_andn2_b64 vcc, exec, s[10:11]
	s_cbranch_vccnz .LBB0_831
	s_barrier
	s_branch .LBB0_831

.LBB0_871:
	v_lshl_add_u32 v128, s45, 8, v158
	v_lshl_add_u32 v150, s44, 8, v156
	v_ashrrev_i32_e32 v129, 31, v128
	v_mov_b64_e32 v[152:153], s[12:13]
	v_mad_i64_i32 v[130:131], s[0:1], v150, s40, v[152:153]
	v_lshlrev_b64 v[148:149], 1, v[128:129]
	v_lshl_add_u64 v[128:129], v[130:131], 0, v[148:149]
	global_load_dwordx4 v[162:165], v[128:129], off nt
	global_load_dwordx4 v[166:169], v[128:129], off offset:256 nt
	v_ashrrev_i32_e32 v151, 31, v150
	v_readlane_b32 s2, v235, 19
	v_lshlrev_b64 v[128:129], 12, v[150:151]
	v_readlane_b32 s3, v235, 20
	s_and_b64 vcc, exec, s[6:7]
	s_waitcnt vmcnt(0)
	v_lshlrev_b32_e32 v151, 16, v162
	v_lshl_add_u64 v[128:129], s[2:3], 0, v[128:129]
	v_lshl_add_u64 v[178:179], v[128:129], 0, v[148:149]
	global_load_dwordx4 v[170:173], v[178:179], off nt
	global_load_dwordx4 v[174:177], v[178:179], off offset:256 nt
	v_and_b32_e32 v162, 0xffff0000, v162
	v_lshlrev_b32_e32 v183, 16, v163
	v_and_b32_e32 v163, 0xffff0000, v163
	v_lshlrev_b32_e32 v184, 16, v164
	v_and_b32_e32 v164, 0xffff0000, v164
	v_lshlrev_b32_e32 v185, 16, v165
	v_and_b32_e32 v165, 0xffff0000, v165
	v_mul_f32_e32 v151, 0xbfb8aa3b, v151
	v_mul_f32_e32 v162, 0xbfb8aa3b, v162
	v_mul_f32_e32 v183, 0xbfb8aa3b, v183
	v_mul_f32_e32 v163, 0xbfb8aa3b, v163
	v_mul_f32_e32 v184, 0xbfb8aa3b, v184
	v_mul_f32_e32 v164, 0xbfb8aa3b, v164
	v_mul_f32_e32 v185, 0xbfb8aa3b, v185
	v_mul_f32_e32 v165, 0xbfb8aa3b, v165
	v_exp_f32_e32 v151, v151
	v_exp_f32_e32 v162, v162
	v_exp_f32_e32 v183, v183
	v_exp_f32_e32 v163, v163
	v_exp_f32_e32 v184, v184
	v_exp_f32_e32 v164, v164
	v_exp_f32_e32 v185, v185
	v_exp_f32_e32 v165, v165
	v_or_b32_e32 v128, 16, v150
	v_ashrrev_i32_e32 v129, 31, v128
	v_add_f32_e32 v151, 1.0, v151
	v_add_f32_e32 v162, 1.0, v162
	v_add_f32_e32 v183, 1.0, v183
	v_add_f32_e32 v163, 1.0, v163
	v_add_f32_e32 v184, 1.0, v184
	v_add_f32_e32 v164, 1.0, v164
	v_add_f32_e32 v185, 1.0, v185
	v_add_f32_e32 v165, 1.0, v165
	v_mad_i64_i32 v[130:131], s[0:1], v128, s40, v[152:153]
	v_lshlrev_b64 v[128:129], 12, v[128:129]
	v_rcp_f32_e32 v151, v151
	v_rcp_f32_e32 v162, v162
	v_rcp_f32_e32 v183, v183
	v_rcp_f32_e32 v163, v163
	v_rcp_f32_e32 v184, v184
	v_rcp_f32_e32 v164, v164
	v_rcp_f32_e32 v185, v185
	v_rcp_f32_e32 v165, v165
	v_lshl_add_u64 v[128:129], s[2:3], 0, v[128:129]
	v_lshl_add_u64 v[154:155], v[128:129], 0, v[148:149]
	v_lshl_add_u64 v[180:181], v[130:131], 0, v[148:149]
	global_load_dwordx4 v[128:131], v[154:155], off nt
	v_lshlrev_b32_e32 v186, 16, v166
	s_waitcnt vmcnt(2)
	v_lshlrev_b32_e32 v187, 16, v170
	v_and_b32_e32 v170, 0xffff0000, v170
	v_lshlrev_b32_e32 v188, 16, v171
	v_and_b32_e32 v171, 0xffff0000, v171
	v_lshlrev_b32_e32 v189, 16, v172
	v_and_b32_e32 v172, 0xffff0000, v172
	v_lshlrev_b32_e32 v190, 16, v173
	v_and_b32_e32 v173, 0xffff0000, v173
	v_fmac_f32_e32 v187, v124, v151
	v_fmac_f32_e32 v170, v125, v162
	v_fmac_f32_e32 v188, v126, v183
	v_fmac_f32_e32 v171, v127, v163
	v_fmac_f32_e32 v189, v120, v184
	v_fmac_f32_e32 v172, v121, v164
	v_fmac_f32_e32 v190, v122, v185
	v_fmac_f32_e32 v173, v123, v165
	v_cvt_pk_bf16_f32 v120, v187, v170
	v_cvt_pk_bf16_f32 v121, v188, v171
	v_cvt_pk_bf16_f32 v122, v189, v172
	v_cvt_pk_bf16_f32 v123, v190, v173
	global_store_dwordx4 v[178:179], v[120:123], off
	global_load_dwordx4 v[120:123], v[180:181], off nt
	v_and_b32_e32 v124, 0xffff0000, v166
	v_lshlrev_b32_e32 v125, 16, v167
	v_and_b32_e32 v126, 0xffff0000, v167
	v_lshlrev_b32_e32 v127, 16, v168
	v_and_b32_e32 v151, 0xffff0000, v168
	v_lshlrev_b32_e32 v162, 16, v169
	v_and_b32_e32 v163, 0xffff0000, v169
	v_mul_f32_e32 v164, 0xbfb8aa3b, v186
	v_mul_f32_e32 v124, 0xbfb8aa3b, v124
	v_mul_f32_e32 v125, 0xbfb8aa3b, v125
	v_mul_f32_e32 v126, 0xbfb8aa3b, v126
	v_mul_f32_e32 v127, 0xbfb8aa3b, v127
	v_mul_f32_e32 v151, 0xbfb8aa3b, v151
	v_mul_f32_e32 v162, 0xbfb8aa3b, v162
	v_mul_f32_e32 v163, 0xbfb8aa3b, v163
	v_exp_f32_e32 v164, v164
	v_exp_f32_e32 v124, v124
	v_exp_f32_e32 v125, v125
	v_exp_f32_e32 v126, v126
	v_exp_f32_e32 v127, v127
	v_exp_f32_e32 v151, v151
	v_exp_f32_e32 v162, v162
	v_exp_f32_e32 v163, v163
	v_add_f32_e32 v164, 1.0, v164
	v_add_f32_e32 v124, 1.0, v124
	v_add_f32_e32 v125, 1.0, v125
	v_add_f32_e32 v126, 1.0, v126
	v_add_f32_e32 v127, 1.0, v127
	v_add_f32_e32 v151, 1.0, v151
	v_add_f32_e32 v162, 1.0, v162
	v_add_f32_e32 v163, 1.0, v163
	v_rcp_f32_e32 v164, v164
	v_rcp_f32_e32 v124, v124
	v_rcp_f32_e32 v125, v125
	v_rcp_f32_e32 v126, v126
	v_rcp_f32_e32 v127, v127
	v_rcp_f32_e32 v151, v151
	v_rcp_f32_e32 v162, v162
	v_rcp_f32_e32 v163, v163
	s_waitcnt vmcnt(3)
	v_lshlrev_b32_e32 v165, 16, v174
	v_and_b32_e32 v166, 0xffff0000, v174
	v_lshlrev_b32_e32 v167, 16, v175
	v_and_b32_e32 v168, 0xffff0000, v175
	v_lshlrev_b32_e32 v169, 16, v176
	v_and_b32_e32 v170, 0xffff0000, v176
	v_lshlrev_b32_e32 v171, 16, v177
	v_and_b32_e32 v172, 0xffff0000, v177
	v_fmac_f32_e32 v165, v116, v164
	v_fmac_f32_e32 v166, v117, v124
	v_fmac_f32_e32 v167, v118, v125
	v_fmac_f32_e32 v168, v119, v126
	v_fmac_f32_e32 v169, v112, v127
	v_fmac_f32_e32 v170, v113, v151
	v_fmac_f32_e32 v171, v114, v162
	v_fmac_f32_e32 v172, v115, v163
	v_cvt_pk_bf16_f32 v112, v165, v166
	v_cvt_pk_bf16_f32 v113, v167, v168
	v_cvt_pk_bf16_f32 v114, v169, v170
	v_cvt_pk_bf16_f32 v115, v171, v172
	global_store_dwordx4 v[178:179], v[112:115], off offset:256
	global_load_dwordx4 v[112:115], v[180:181], off offset:256 nt
	s_nop 0
	global_load_dwordx4 v[116:119], v[154:155], off offset:256 nt
	s_waitcnt vmcnt(5)
	v_lshlrev_b32_e32 v151, 16, v128
	s_waitcnt vmcnt(3)
	v_lshlrev_b32_e32 v124, 16, v120
	v_and_b32_e32 v120, 0xffff0000, v120
	v_mul_f32_e32 v124, 0xbfb8aa3b, v124
	v_lshlrev_b32_e32 v125, 16, v121
	v_mul_f32_e32 v120, 0xbfb8aa3b, v120
	v_exp_f32_e32 v124, v124
	v_and_b32_e32 v121, 0xffff0000, v121
	v_mul_f32_e32 v125, 0xbfb8aa3b, v125
	v_exp_f32_e32 v120, v120
	v_lshlrev_b32_e32 v126, 16, v122
	v_and_b32_e32 v122, 0xffff0000, v122
	v_mul_f32_e32 v121, 0xbfb8aa3b, v121
	v_exp_f32_e32 v125, v125
	v_lshlrev_b32_e32 v127, 16, v123
	v_and_b32_e32 v123, 0xffff0000, v123
	v_mul_f32_e32 v126, 0xbfb8aa3b, v126
	v_mul_f32_e32 v122, 0xbfb8aa3b, v122
	v_exp_f32_e32 v121, v121
	v_mul_f32_e32 v127, 0xbfb8aa3b, v127
	v_mul_f32_e32 v123, 0xbfb8aa3b, v123
	v_exp_f32_e32 v126, v126
	v_exp_f32_e32 v122, v122
	v_add_f32_e32 v124, 1.0, v124
	v_exp_f32_e32 v127, v127
	v_exp_f32_e32 v123, v123
	v_add_f32_e32 v120, 1.0, v120
	v_rcp_f32_e32 v124, v124
	v_add_f32_e32 v125, 1.0, v125
	v_rcp_f32_e32 v120, v120
	v_add_f32_e32 v121, 1.0, v121
	v_rcp_f32_e32 v125, v125
	v_add_f32_e32 v126, 1.0, v126
	v_add_f32_e32 v122, 1.0, v122
	v_rcp_f32_e32 v121, v121
	v_rcp_f32_e32 v126, v126
	v_rcp_f32_e32 v122, v122
	v_add_f32_e32 v127, 1.0, v127
	v_add_f32_e32 v123, 1.0, v123
	v_fmac_f32_e32 v151, v108, v124
	v_and_b32_e32 v108, 0xffff0000, v128
	v_rcp_f32_e32 v127, v127
	v_rcp_f32_e32 v123, v123
	v_fmac_f32_e32 v108, v109, v120
	v_lshlrev_b32_e32 v109, 16, v129
	v_fmac_f32_e32 v109, v110, v125
	v_and_b32_e32 v110, 0xffff0000, v129
	v_fmac_f32_e32 v110, v111, v121
	v_lshlrev_b32_e32 v111, 16, v130
	v_and_b32_e32 v120, 0xffff0000, v130
	v_fmac_f32_e32 v111, v104, v126
	v_fmac_f32_e32 v120, v105, v122
	v_lshlrev_b32_e32 v121, 16, v131
	v_and_b32_e32 v122, 0xffff0000, v131
	v_cvt_pk_bf16_f32 v104, v151, v108
	v_fmac_f32_e32 v121, v106, v127
	v_fmac_f32_e32 v122, v107, v123
	v_cvt_pk_bf16_f32 v105, v109, v110
	v_cvt_pk_bf16_f32 v106, v111, v120
	v_cvt_pk_bf16_f32 v107, v121, v122
	global_store_dwordx4 v[154:155], v[104:107], off
	s_waitcnt vmcnt(2)
	v_and_b32_e32 v111, 0xffff0000, v113
	v_mul_f32_e32 v111, 0xbfb8aa3b, v111
	v_lshlrev_b32_e32 v104, 16, v112
	v_mul_f32_e32 v104, 0xbfb8aa3b, v104
	v_exp_f32_e32 v105, v104
	v_and_b32_e32 v104, 0xffff0000, v112
	v_mul_f32_e32 v110, 0xbfb8aa3b, v104
	v_or_b32_e32 v104, 32, v150
	v_mad_i64_i32 v[106:107], s[0:1], v104, s40, v[152:153]
	v_exp_f32_e32 v110, v110
	v_lshl_add_u64 v[120:121], v[106:107], 0, v[148:149]
	global_load_dwordx4 v[106:109], v[120:121], off nt
	v_add_f32_e32 v105, 1.0, v105
	v_rcp_f32_e32 v122, v105
	v_add_f32_e32 v105, 1.0, v110
	v_lshlrev_b32_e32 v110, 16, v113
	v_mul_f32_e32 v110, 0xbfb8aa3b, v110
	v_exp_f32_e32 v110, v110
	v_exp_f32_e32 v111, v111
	v_rcp_f32_e32 v123, v105
	s_waitcnt vmcnt(2)
	v_lshlrev_b32_e32 v128, 16, v116
	v_add_f32_e32 v105, 1.0, v110
	v_lshlrev_b32_e32 v110, 16, v114
	v_rcp_f32_e32 v124, v105
	v_add_f32_e32 v105, 1.0, v111
	v_mul_f32_e32 v110, 0xbfb8aa3b, v110
	v_and_b32_e32 v111, 0xffff0000, v114
	v_exp_f32_e32 v110, v110
	v_mul_f32_e32 v111, 0xbfb8aa3b, v111
	v_exp_f32_e32 v111, v111
	v_rcp_f32_e32 v114, v105
	v_add_f32_e32 v105, 1.0, v110
	v_lshlrev_b32_e32 v110, 16, v115
	v_rcp_f32_e32 v125, v105
	v_add_f32_e32 v105, 1.0, v111
	v_mul_f32_e32 v110, 0xbfb8aa3b, v110
	v_and_b32_e32 v111, 0xffff0000, v115
	v_exp_f32_e32 v110, v110
	v_mul_f32_e32 v111, 0xbfb8aa3b, v111
	v_exp_f32_e32 v111, v111
	v_rcp_f32_e32 v115, v105
	v_add_f32_e32 v105, 1.0, v110
	v_rcp_f32_e32 v126, v105
	v_add_f32_e32 v105, 1.0, v111
	v_rcp_f32_e32 v127, v105
	v_ashrrev_i32_e32 v105, 31, v104
	v_lshlrev_b64 v[104:105], 12, v[104:105]
	v_lshl_add_u64 v[104:105], s[2:3], 0, v[104:105]
	v_lshl_add_u64 v[104:105], v[104:105], 0, v[148:149]
	global_load_dwordx4 v[110:113], v[104:105], off nt
	v_fmac_f32_e32 v128, v100, v122
	v_and_b32_e32 v100, 0xffff0000, v116
	v_fmac_f32_e32 v100, v101, v123
	v_lshlrev_b32_e32 v101, 16, v117
	v_fmac_f32_e32 v101, v102, v124
	v_and_b32_e32 v102, 0xffff0000, v117
	v_fmac_f32_e32 v102, v103, v114
	v_and_b32_e32 v114, 0xffff0000, v118
	v_lshlrev_b32_e32 v103, 16, v118
	v_fmac_f32_e32 v114, v97, v115
	v_lshlrev_b32_e32 v115, 16, v119
	v_and_b32_e32 v116, 0xffff0000, v119
	v_fmac_f32_e32 v103, v96, v125
	v_fmac_f32_e32 v115, v98, v126
	v_fmac_f32_e32 v116, v99, v127
	v_cvt_pk_bf16_f32 v96, v128, v100
	v_cvt_pk_bf16_f32 v97, v101, v102
	v_cvt_pk_bf16_f32 v98, v103, v114
	v_cvt_pk_bf16_f32 v99, v115, v116
	global_store_dwordx4 v[154:155], v[96:99], off offset:256
	global_load_dwordx4 v[96:99], v[120:121], off offset:256 nt
	s_waitcnt vmcnt(3)
	v_lshlrev_b32_e32 v100, 16, v106
	v_mul_f32_e32 v100, 0xbfb8aa3b, v100
	v_and_b32_e32 v101, 0xffff0000, v106
	v_exp_f32_e32 v100, v100
	v_mul_f32_e32 v101, 0xbfb8aa3b, v101
	v_exp_f32_e32 v101, v101
	v_and_b32_e32 v102, 0xffff0000, v107
	v_add_f32_e32 v100, 1.0, v100
	v_rcp_f32_e32 v106, v100
	v_add_f32_e32 v100, 1.0, v101
	v_lshlrev_b32_e32 v101, 16, v107
	v_mul_f32_e32 v101, 0xbfb8aa3b, v101
	v_exp_f32_e32 v101, v101
	v_mul_f32_e32 v102, 0xbfb8aa3b, v102
	v_exp_f32_e32 v102, v102
	v_rcp_f32_e32 v107, v100
	v_add_f32_e32 v100, 1.0, v101
	v_rcp_f32_e32 v114, v100
	v_add_f32_e32 v100, 1.0, v102
	v_rcp_f32_e32 v115, v100
	v_lshlrev_b32_e32 v100, 16, v108
	v_mul_f32_e32 v100, 0xbfb8aa3b, v100
	v_exp_f32_e32 v100, v100
	v_and_b32_e32 v101, 0xffff0000, v108
	v_mul_f32_e32 v101, 0xbfb8aa3b, v101
	v_lshlrev_b32_e32 v117, 16, v109
	v_add_f32_e32 v100, 1.0, v100
	v_and_b32_e32 v109, 0xffff0000, v109
	v_exp_f32_e32 v108, v101
	v_rcp_f32_e32 v116, v100
	global_load_dwordx4 v[100:103], v[104:105], off offset:256 nt
	v_mul_f32_e32 v117, 0xbfb8aa3b, v117
	v_mul_f32_e32 v109, 0xbfb8aa3b, v109
	v_exp_f32_e32 v117, v117
	v_exp_f32_e32 v109, v109
	v_add_f32_e32 v108, 1.0, v108
	v_rcp_f32_e32 v108, v108
	v_add_f32_e32 v117, 1.0, v117
	s_waitcnt vmcnt(3)
	v_lshlrev_b32_e32 v118, 16, v110
	v_add_f32_e32 v109, 1.0, v109
	v_fmac_f32_e32 v118, v92, v106
	v_and_b32_e32 v92, 0xffff0000, v110
	v_rcp_f32_e32 v117, v117
	v_rcp_f32_e32 v109, v109
	v_fmac_f32_e32 v92, v93, v107
	v_lshlrev_b32_e32 v93, 16, v111
	v_fmac_f32_e32 v93, v94, v114
	v_and_b32_e32 v94, 0xffff0000, v111
	v_fmac_f32_e32 v94, v95, v115
	v_lshlrev_b32_e32 v95, 16, v112
	v_and_b32_e32 v106, 0xffff0000, v112
	v_fmac_f32_e32 v95, v88, v116
	v_fmac_f32_e32 v106, v89, v108
	v_lshlrev_b32_e32 v107, 16, v113
	v_and_b32_e32 v108, 0xffff0000, v113
	v_cvt_pk_bf16_f32 v88, v118, v92
	v_fmac_f32_e32 v107, v90, v117
	v_fmac_f32_e32 v108, v91, v109
	v_cvt_pk_bf16_f32 v89, v93, v94
	v_cvt_pk_bf16_f32 v90, v95, v106
	v_cvt_pk_bf16_f32 v91, v107, v108
	global_store_dwordx4 v[104:105], v[88:91], off
	s_waitcnt vmcnt(2)
	v_and_b32_e32 v95, 0xffff0000, v97
	v_mul_f32_e32 v95, 0xbfb8aa3b, v95
	v_lshlrev_b32_e32 v88, 16, v96
	v_mul_f32_e32 v88, 0xbfb8aa3b, v88
	v_exp_f32_e32 v89, v88
	v_and_b32_e32 v88, 0xffff0000, v96
	v_mul_f32_e32 v94, 0xbfb8aa3b, v88
	v_or_b32_e32 v88, 48, v150
	v_mad_i64_i32 v[90:91], s[0:1], v88, s40, v[152:153]
	v_lshl_add_u64 v[106:107], v[90:91], 0, v[148:149]
	global_load_dwordx4 v[90:93], v[106:107], off nt
	v_exp_f32_e32 v94, v94
	v_add_f32_e32 v89, 1.0, v89
	v_rcp_f32_e32 v108, v89
	v_exp_f32_e32 v95, v95
	v_add_f32_e32 v89, 1.0, v94
	v_lshlrev_b32_e32 v94, 16, v97
	v_mul_f32_e32 v94, 0xbfb8aa3b, v94
	v_exp_f32_e32 v94, v94
	v_rcp_f32_e32 v109, v89
	v_add_f32_e32 v89, 1.0, v94
	v_lshlrev_b32_e32 v94, 16, v98
	v_rcp_f32_e32 v110, v89
	v_add_f32_e32 v89, 1.0, v95
	v_mul_f32_e32 v94, 0xbfb8aa3b, v94
	v_and_b32_e32 v95, 0xffff0000, v98
	v_exp_f32_e32 v94, v94
	v_mul_f32_e32 v95, 0xbfb8aa3b, v95
	v_exp_f32_e32 v95, v95
	v_rcp_f32_e32 v98, v89
	v_add_f32_e32 v89, 1.0, v94
	v_lshlrev_b32_e32 v94, 16, v99
	v_rcp_f32_e32 v111, v89
	v_add_f32_e32 v89, 1.0, v95
	v_mul_f32_e32 v94, 0xbfb8aa3b, v94
	v_and_b32_e32 v95, 0xffff0000, v99
	v_exp_f32_e32 v94, v94
	v_mul_f32_e32 v95, 0xbfb8aa3b, v95
	v_exp_f32_e32 v95, v95
	v_rcp_f32_e32 v99, v89
	v_add_f32_e32 v89, 1.0, v94
	v_rcp_f32_e32 v112, v89
	v_add_f32_e32 v89, 1.0, v95
	v_rcp_f32_e32 v113, v89
	v_ashrrev_i32_e32 v89, 31, v88
	v_lshlrev_b64 v[88:89], 12, v[88:89]
	v_lshl_add_u64 v[88:89], s[2:3], 0, v[88:89]
	s_waitcnt vmcnt(2)
	v_lshlrev_b32_e32 v114, 16, v100
	v_lshl_add_u64 v[88:89], v[88:89], 0, v[148:149]
	global_load_dwordx4 v[94:97], v[88:89], off nt
	v_fmac_f32_e32 v114, v84, v108
	v_and_b32_e32 v84, 0xffff0000, v100
	v_fmac_f32_e32 v84, v85, v109
	v_lshlrev_b32_e32 v85, 16, v101
	v_fmac_f32_e32 v85, v86, v110
	v_and_b32_e32 v86, 0xffff0000, v101
	v_fmac_f32_e32 v86, v87, v98
	v_and_b32_e32 v98, 0xffff0000, v102
	v_lshlrev_b32_e32 v87, 16, v102
	v_fmac_f32_e32 v98, v81, v99
	v_lshlrev_b32_e32 v99, 16, v103
	v_and_b32_e32 v100, 0xffff0000, v103
	v_fmac_f32_e32 v87, v80, v111
	v_fmac_f32_e32 v99, v82, v112
	v_fmac_f32_e32 v100, v83, v113
	v_cvt_pk_bf16_f32 v80, v114, v84
	v_cvt_pk_bf16_f32 v81, v85, v86
	v_cvt_pk_bf16_f32 v82, v87, v98
	v_cvt_pk_bf16_f32 v83, v99, v100
	global_store_dwordx4 v[104:105], v[80:83], off offset:256
	global_load_dwordx4 v[80:83], v[106:107], off offset:256 nt
	s_waitcnt vmcnt(3)
	v_lshlrev_b32_e32 v84, 16, v90
	v_mul_f32_e32 v84, 0xbfb8aa3b, v84
	v_and_b32_e32 v85, 0xffff0000, v90
	v_exp_f32_e32 v84, v84
	v_mul_f32_e32 v85, 0xbfb8aa3b, v85
	v_exp_f32_e32 v85, v85
	v_and_b32_e32 v86, 0xffff0000, v91
	v_add_f32_e32 v84, 1.0, v84
	v_rcp_f32_e32 v90, v84
	v_add_f32_e32 v84, 1.0, v85
	v_lshlrev_b32_e32 v85, 16, v91
	v_mul_f32_e32 v85, 0xbfb8aa3b, v85
	v_exp_f32_e32 v85, v85
	v_mul_f32_e32 v86, 0xbfb8aa3b, v86
	v_exp_f32_e32 v86, v86
	v_rcp_f32_e32 v91, v84
	v_add_f32_e32 v84, 1.0, v85
	v_rcp_f32_e32 v98, v84
	v_add_f32_e32 v84, 1.0, v86
	v_rcp_f32_e32 v99, v84
	v_lshlrev_b32_e32 v84, 16, v92
	v_mul_f32_e32 v84, 0xbfb8aa3b, v84
	v_exp_f32_e32 v84, v84
	v_and_b32_e32 v85, 0xffff0000, v92
	v_mul_f32_e32 v85, 0xbfb8aa3b, v85
	v_exp_f32_e32 v92, v85
	v_add_f32_e32 v84, 1.0, v84
	v_rcp_f32_e32 v100, v84
	global_load_dwordx4 v[84:87], v[88:89], off offset:256 nt
	v_lshlrev_b32_e32 v101, 16, v93
	v_and_b32_e32 v93, 0xffff0000, v93
	v_mul_f32_e32 v101, 0xbfb8aa3b, v101
	v_mul_f32_e32 v93, 0xbfb8aa3b, v93
	v_exp_f32_e32 v101, v101
	v_exp_f32_e32 v93, v93
	v_add_f32_e32 v92, 1.0, v92
	v_rcp_f32_e32 v92, v92
	v_add_f32_e32 v101, 1.0, v101
	v_add_f32_e32 v93, 1.0, v93
	v_rcp_f32_e32 v101, v101
	v_rcp_f32_e32 v93, v93
	s_waitcnt vmcnt(3)
	v_lshlrev_b32_e32 v102, 16, v94
	v_fmac_f32_e32 v102, v76, v90
	v_and_b32_e32 v76, 0xffff0000, v94
	v_fmac_f32_e32 v76, v77, v91
	v_lshlrev_b32_e32 v77, 16, v95
	v_fmac_f32_e32 v77, v78, v98
	v_and_b32_e32 v78, 0xffff0000, v95
	v_fmac_f32_e32 v78, v79, v99
	v_lshlrev_b32_e32 v79, 16, v96
	v_and_b32_e32 v90, 0xffff0000, v96
	v_fmac_f32_e32 v79, v72, v100
	v_fmac_f32_e32 v90, v73, v92
	v_lshlrev_b32_e32 v91, 16, v97
	v_and_b32_e32 v92, 0xffff0000, v97
	v_cvt_pk_bf16_f32 v72, v102, v76
	v_fmac_f32_e32 v91, v74, v101
	v_fmac_f32_e32 v92, v75, v93
	v_cvt_pk_bf16_f32 v73, v77, v78
	v_cvt_pk_bf16_f32 v74, v79, v90
	v_cvt_pk_bf16_f32 v75, v91, v92
	global_store_dwordx4 v[88:89], v[72:75], off
	s_waitcnt vmcnt(2)
	v_and_b32_e32 v79, 0xffff0000, v81
	v_mul_f32_e32 v79, 0xbfb8aa3b, v79
	v_lshlrev_b32_e32 v72, 16, v80
	v_mul_f32_e32 v72, 0xbfb8aa3b, v72
	v_exp_f32_e32 v73, v72
	v_and_b32_e32 v72, 0xffff0000, v80
	v_mul_f32_e32 v78, 0xbfb8aa3b, v72
	v_add_u32_e32 v72, 0x80, v150
	v_mad_i64_i32 v[74:75], s[0:1], v72, s40, v[152:153]
	v_exp_f32_e32 v78, v78
	v_lshl_add_u64 v[90:91], v[74:75], 0, v[148:149]
	global_load_dwordx4 v[74:77], v[90:91], off nt
	v_add_f32_e32 v73, 1.0, v73
	v_rcp_f32_e32 v92, v73
	v_add_f32_e32 v73, 1.0, v78
	v_lshlrev_b32_e32 v78, 16, v81
	v_mul_f32_e32 v78, 0xbfb8aa3b, v78
	v_exp_f32_e32 v78, v78
	v_exp_f32_e32 v79, v79
	v_rcp_f32_e32 v93, v73
	v_add_f32_e32 v73, 1.0, v78
	v_lshlrev_b32_e32 v78, 16, v82
	v_rcp_f32_e32 v94, v73
	v_add_f32_e32 v73, 1.0, v79
	v_mul_f32_e32 v78, 0xbfb8aa3b, v78
	v_and_b32_e32 v79, 0xffff0000, v82
	v_exp_f32_e32 v78, v78
	v_mul_f32_e32 v79, 0xbfb8aa3b, v79
	v_exp_f32_e32 v79, v79
	v_rcp_f32_e32 v82, v73
	v_add_f32_e32 v73, 1.0, v78
	v_lshlrev_b32_e32 v78, 16, v83
	v_rcp_f32_e32 v95, v73
	v_add_f32_e32 v73, 1.0, v79
	v_mul_f32_e32 v78, 0xbfb8aa3b, v78
	v_and_b32_e32 v79, 0xffff0000, v83
	v_exp_f32_e32 v78, v78
	v_mul_f32_e32 v79, 0xbfb8aa3b, v79
	v_exp_f32_e32 v79, v79
	v_rcp_f32_e32 v83, v73
	v_add_f32_e32 v73, 1.0, v78
	v_rcp_f32_e32 v96, v73
	v_add_f32_e32 v73, 1.0, v79
	v_rcp_f32_e32 v97, v73
	v_ashrrev_i32_e32 v73, 31, v72
	v_lshlrev_b64 v[72:73], 12, v[72:73]
	v_lshl_add_u64 v[72:73], s[2:3], 0, v[72:73]
	s_waitcnt vmcnt(2)
	v_lshlrev_b32_e32 v98, 16, v84
	v_lshl_add_u64 v[72:73], v[72:73], 0, v[148:149]
	global_load_dwordx4 v[78:81], v[72:73], off nt
	v_fmac_f32_e32 v98, v68, v92
	v_and_b32_e32 v68, 0xffff0000, v84
	v_fmac_f32_e32 v68, v69, v93
	v_lshlrev_b32_e32 v69, 16, v85
	v_fmac_f32_e32 v69, v70, v94
	v_and_b32_e32 v70, 0xffff0000, v85
	v_fmac_f32_e32 v70, v71, v82
	v_and_b32_e32 v82, 0xffff0000, v86
	v_lshlrev_b32_e32 v71, 16, v86
	v_fmac_f32_e32 v82, v65, v83
	v_lshlrev_b32_e32 v83, 16, v87
	v_and_b32_e32 v84, 0xffff0000, v87
	v_fmac_f32_e32 v71, v64, v95
	v_fmac_f32_e32 v83, v66, v96
	v_fmac_f32_e32 v84, v67, v97
	v_cvt_pk_bf16_f32 v64, v98, v68
	v_cvt_pk_bf16_f32 v65, v69, v70
	v_cvt_pk_bf16_f32 v66, v71, v82
	v_cvt_pk_bf16_f32 v67, v83, v84
	global_store_dwordx4 v[88:89], v[64:67], off offset:256
	global_load_dwordx4 v[64:67], v[90:91], off offset:256 nt
	s_waitcnt vmcnt(3)
	v_lshlrev_b32_e32 v68, 16, v74
	v_mul_f32_e32 v68, 0xbfb8aa3b, v68
	v_and_b32_e32 v69, 0xffff0000, v74
	v_exp_f32_e32 v68, v68
	v_mul_f32_e32 v69, 0xbfb8aa3b, v69
	v_exp_f32_e32 v69, v69
	v_and_b32_e32 v70, 0xffff0000, v75
	v_add_f32_e32 v68, 1.0, v68
	v_rcp_f32_e32 v74, v68
	v_add_f32_e32 v68, 1.0, v69
	v_lshlrev_b32_e32 v69, 16, v75
	v_mul_f32_e32 v69, 0xbfb8aa3b, v69
	v_exp_f32_e32 v69, v69
	v_mul_f32_e32 v70, 0xbfb8aa3b, v70
	v_exp_f32_e32 v70, v70
	v_rcp_f32_e32 v75, v68
	v_add_f32_e32 v68, 1.0, v69
	v_rcp_f32_e32 v82, v68
	v_add_f32_e32 v68, 1.0, v70
	v_rcp_f32_e32 v83, v68
	v_lshlrev_b32_e32 v68, 16, v76
	v_mul_f32_e32 v68, 0xbfb8aa3b, v68
	v_exp_f32_e32 v68, v68
	v_and_b32_e32 v69, 0xffff0000, v76
	v_mul_f32_e32 v69, 0xbfb8aa3b, v69
	v_lshlrev_b32_e32 v85, 16, v77
	v_add_f32_e32 v68, 1.0, v68
	v_and_b32_e32 v77, 0xffff0000, v77
	v_exp_f32_e32 v76, v69
	v_rcp_f32_e32 v84, v68
	global_load_dwordx4 v[68:71], v[72:73], off offset:256 nt
	v_mul_f32_e32 v85, 0xbfb8aa3b, v85
	v_mul_f32_e32 v77, 0xbfb8aa3b, v77
	v_exp_f32_e32 v85, v85
	v_exp_f32_e32 v77, v77
	v_add_f32_e32 v76, 1.0, v76
	v_rcp_f32_e32 v76, v76
	v_add_f32_e32 v85, 1.0, v85
	v_add_f32_e32 v77, 1.0, v77
	s_waitcnt vmcnt(3)
	v_lshlrev_b32_e32 v86, 16, v78
	v_fmac_f32_e32 v86, v60, v74
	v_and_b32_e32 v60, 0xffff0000, v78
	v_rcp_f32_e32 v85, v85
	v_rcp_f32_e32 v77, v77
	v_fmac_f32_e32 v60, v61, v75
	v_lshlrev_b32_e32 v61, 16, v79
	v_fmac_f32_e32 v61, v62, v82
	v_and_b32_e32 v62, 0xffff0000, v79
	v_fmac_f32_e32 v62, v63, v83
	v_lshlrev_b32_e32 v63, 16, v80
	v_and_b32_e32 v74, 0xffff0000, v80
	v_fmac_f32_e32 v63, v56, v84
	v_fmac_f32_e32 v74, v57, v76
	v_lshlrev_b32_e32 v75, 16, v81
	v_and_b32_e32 v76, 0xffff0000, v81
	v_cvt_pk_bf16_f32 v56, v86, v60
	v_fmac_f32_e32 v75, v58, v85
	v_fmac_f32_e32 v76, v59, v77
	v_cvt_pk_bf16_f32 v57, v61, v62
	v_cvt_pk_bf16_f32 v58, v63, v74
	v_cvt_pk_bf16_f32 v59, v75, v76
	global_store_dwordx4 v[72:73], v[56:59], off
	s_waitcnt vmcnt(2)
	v_and_b32_e32 v63, 0xffff0000, v65
	v_mul_f32_e32 v63, 0xbfb8aa3b, v63
	v_lshlrev_b32_e32 v56, 16, v64
	v_mul_f32_e32 v56, 0xbfb8aa3b, v56
	v_exp_f32_e32 v57, v56
	v_and_b32_e32 v56, 0xffff0000, v64
	v_mul_f32_e32 v62, 0xbfb8aa3b, v56
	v_add_u32_e32 v56, 0x90, v150
	v_mad_i64_i32 v[58:59], s[0:1], v56, s40, v[152:153]
	v_lshl_add_u64 v[74:75], v[58:59], 0, v[148:149]
	global_load_dwordx4 v[58:61], v[74:75], off nt
	v_exp_f32_e32 v62, v62
	v_add_f32_e32 v57, 1.0, v57
	v_rcp_f32_e32 v76, v57
	v_exp_f32_e32 v63, v63
	v_add_f32_e32 v57, 1.0, v62
	v_lshlrev_b32_e32 v62, 16, v65
	v_mul_f32_e32 v62, 0xbfb8aa3b, v62
	v_exp_f32_e32 v62, v62
	v_rcp_f32_e32 v77, v57
	v_add_f32_e32 v57, 1.0, v62
	v_lshlrev_b32_e32 v62, 16, v66
	v_rcp_f32_e32 v78, v57
	v_add_f32_e32 v57, 1.0, v63
	v_mul_f32_e32 v62, 0xbfb8aa3b, v62
	v_and_b32_e32 v63, 0xffff0000, v66
	v_exp_f32_e32 v62, v62
	v_mul_f32_e32 v63, 0xbfb8aa3b, v63
	v_exp_f32_e32 v63, v63
	v_rcp_f32_e32 v66, v57
	v_add_f32_e32 v57, 1.0, v62
	v_lshlrev_b32_e32 v62, 16, v67
	v_rcp_f32_e32 v79, v57
	v_add_f32_e32 v57, 1.0, v63
	v_mul_f32_e32 v62, 0xbfb8aa3b, v62
	v_and_b32_e32 v63, 0xffff0000, v67
	v_exp_f32_e32 v62, v62
	v_mul_f32_e32 v63, 0xbfb8aa3b, v63
	v_exp_f32_e32 v63, v63
	v_rcp_f32_e32 v67, v57
	v_add_f32_e32 v57, 1.0, v62
	v_rcp_f32_e32 v80, v57
	v_add_f32_e32 v57, 1.0, v63
	v_rcp_f32_e32 v81, v57
	v_ashrrev_i32_e32 v57, 31, v56
	v_lshlrev_b64 v[56:57], 12, v[56:57]
	v_lshl_add_u64 v[56:57], s[2:3], 0, v[56:57]
	s_waitcnt vmcnt(2)
	v_lshlrev_b32_e32 v82, 16, v68
	v_lshl_add_u64 v[56:57], v[56:57], 0, v[148:149]
	global_load_dwordx4 v[62:65], v[56:57], off nt
	v_fmac_f32_e32 v82, v52, v76
	v_and_b32_e32 v52, 0xffff0000, v68
	v_fmac_f32_e32 v52, v53, v77
	v_lshlrev_b32_e32 v53, 16, v69
	v_fmac_f32_e32 v53, v54, v78
	v_and_b32_e32 v54, 0xffff0000, v69
	v_fmac_f32_e32 v54, v55, v66
	v_and_b32_e32 v66, 0xffff0000, v70
	v_lshlrev_b32_e32 v55, 16, v70
	v_fmac_f32_e32 v66, v49, v67
	v_lshlrev_b32_e32 v67, 16, v71
	v_and_b32_e32 v68, 0xffff0000, v71
	v_fmac_f32_e32 v55, v48, v79
	v_fmac_f32_e32 v67, v50, v80
	v_fmac_f32_e32 v68, v51, v81
	v_cvt_pk_bf16_f32 v48, v82, v52
	v_cvt_pk_bf16_f32 v49, v53, v54
	v_cvt_pk_bf16_f32 v50, v55, v66
	v_cvt_pk_bf16_f32 v51, v67, v68
	global_store_dwordx4 v[72:73], v[48:51], off offset:256
	global_load_dwordx4 v[48:51], v[74:75], off offset:256 nt
	s_waitcnt vmcnt(3)
	v_lshlrev_b32_e32 v52, 16, v58
	v_mul_f32_e32 v52, 0xbfb8aa3b, v52
	v_and_b32_e32 v53, 0xffff0000, v58
	v_exp_f32_e32 v52, v52
	v_mul_f32_e32 v53, 0xbfb8aa3b, v53
	v_exp_f32_e32 v53, v53
	v_and_b32_e32 v54, 0xffff0000, v59
	v_add_f32_e32 v52, 1.0, v52
	v_rcp_f32_e32 v58, v52
	v_add_f32_e32 v52, 1.0, v53
	v_lshlrev_b32_e32 v53, 16, v59
	v_mul_f32_e32 v53, 0xbfb8aa3b, v53
	v_exp_f32_e32 v53, v53
	v_mul_f32_e32 v54, 0xbfb8aa3b, v54
	v_exp_f32_e32 v54, v54
	v_rcp_f32_e32 v59, v52
	v_add_f32_e32 v52, 1.0, v53
	v_rcp_f32_e32 v66, v52
	v_add_f32_e32 v52, 1.0, v54
	v_rcp_f32_e32 v67, v52
	v_lshlrev_b32_e32 v52, 16, v60
	v_mul_f32_e32 v52, 0xbfb8aa3b, v52
	v_exp_f32_e32 v52, v52
	v_and_b32_e32 v53, 0xffff0000, v60
	v_mul_f32_e32 v53, 0xbfb8aa3b, v53
	v_exp_f32_e32 v60, v53
	v_add_f32_e32 v52, 1.0, v52
	v_rcp_f32_e32 v68, v52
	global_load_dwordx4 v[52:55], v[56:57], off offset:256 nt
	v_lshlrev_b32_e32 v69, 16, v61
	v_and_b32_e32 v61, 0xffff0000, v61
	v_mul_f32_e32 v69, 0xbfb8aa3b, v69
	v_mul_f32_e32 v61, 0xbfb8aa3b, v61
	v_exp_f32_e32 v69, v69
	v_exp_f32_e32 v61, v61
	v_add_f32_e32 v60, 1.0, v60
	v_rcp_f32_e32 v60, v60
	v_add_f32_e32 v69, 1.0, v69
	v_add_f32_e32 v61, 1.0, v61
	v_rcp_f32_e32 v69, v69
	v_rcp_f32_e32 v61, v61
	s_waitcnt vmcnt(3)
	v_lshlrev_b32_e32 v70, 16, v62
	v_fmac_f32_e32 v70, v44, v58
	v_and_b32_e32 v44, 0xffff0000, v62
	v_fmac_f32_e32 v44, v45, v59
	v_lshlrev_b32_e32 v45, 16, v63
	v_fmac_f32_e32 v45, v46, v66
	v_and_b32_e32 v46, 0xffff0000, v63
	v_fmac_f32_e32 v46, v47, v67
	v_lshlrev_b32_e32 v47, 16, v64
	v_and_b32_e32 v58, 0xffff0000, v64
	v_fmac_f32_e32 v47, v40, v68
	v_fmac_f32_e32 v58, v41, v60
	v_lshlrev_b32_e32 v59, 16, v65
	v_and_b32_e32 v60, 0xffff0000, v65
	v_cvt_pk_bf16_f32 v40, v70, v44
	v_fmac_f32_e32 v59, v42, v69
	v_fmac_f32_e32 v60, v43, v61
	v_cvt_pk_bf16_f32 v41, v45, v46
	v_cvt_pk_bf16_f32 v42, v47, v58
	v_cvt_pk_bf16_f32 v43, v59, v60
	global_store_dwordx4 v[56:57], v[40:43], off
	s_waitcnt vmcnt(2)
	v_and_b32_e32 v47, 0xffff0000, v49
	v_mul_f32_e32 v47, 0xbfb8aa3b, v47
	v_lshlrev_b32_e32 v40, 16, v48
	v_mul_f32_e32 v40, 0xbfb8aa3b, v40
	v_exp_f32_e32 v41, v40
	v_and_b32_e32 v40, 0xffff0000, v48
	v_mul_f32_e32 v46, 0xbfb8aa3b, v40
	v_exp_f32_e32 v46, v46
	v_add_u32_e32 v40, 0xa0, v150
	v_add_f32_e32 v41, 1.0, v41
	v_mad_i64_i32 v[42:43], s[0:1], v40, s40, v[152:153]
	v_rcp_f32_e32 v60, v41
	v_add_f32_e32 v41, 1.0, v46
	v_lshlrev_b32_e32 v46, 16, v49
	v_lshl_add_u64 v[58:59], v[42:43], 0, v[148:149]
	v_mul_f32_e32 v46, 0xbfb8aa3b, v46
	global_load_dwordx4 v[42:45], v[58:59], off nt
	v_exp_f32_e32 v46, v46
	v_exp_f32_e32 v47, v47
	v_rcp_f32_e32 v61, v41
	v_add_f32_e32 v41, 1.0, v46
	v_lshlrev_b32_e32 v46, 16, v50
	v_rcp_f32_e32 v62, v41
	v_add_f32_e32 v41, 1.0, v47
	v_mul_f32_e32 v46, 0xbfb8aa3b, v46
	v_and_b32_e32 v47, 0xffff0000, v50
	v_exp_f32_e32 v46, v46
	v_mul_f32_e32 v47, 0xbfb8aa3b, v47
	v_exp_f32_e32 v47, v47
	v_rcp_f32_e32 v50, v41
	v_add_f32_e32 v41, 1.0, v46
	v_lshlrev_b32_e32 v46, 16, v51
	v_rcp_f32_e32 v63, v41
	v_add_f32_e32 v41, 1.0, v47
	v_mul_f32_e32 v46, 0xbfb8aa3b, v46
	v_and_b32_e32 v47, 0xffff0000, v51
	v_exp_f32_e32 v46, v46
	v_mul_f32_e32 v47, 0xbfb8aa3b, v47
	v_exp_f32_e32 v47, v47
	v_rcp_f32_e32 v51, v41
	v_add_f32_e32 v41, 1.0, v46
	v_rcp_f32_e32 v64, v41
	v_add_f32_e32 v41, 1.0, v47
	v_rcp_f32_e32 v65, v41
	v_ashrrev_i32_e32 v41, 31, v40
	v_lshlrev_b64 v[40:41], 12, v[40:41]
	v_lshl_add_u64 v[40:41], s[2:3], 0, v[40:41]
	s_waitcnt vmcnt(2)
	v_lshlrev_b32_e32 v66, 16, v52
	v_lshl_add_u64 v[40:41], v[40:41], 0, v[148:149]
	global_load_dwordx4 v[46:49], v[40:41], off nt
	v_fmac_f32_e32 v66, v36, v60
	v_and_b32_e32 v36, 0xffff0000, v52
	v_fmac_f32_e32 v36, v37, v61
	v_lshlrev_b32_e32 v37, 16, v53
	v_fmac_f32_e32 v37, v38, v62
	v_and_b32_e32 v38, 0xffff0000, v53
	v_fmac_f32_e32 v38, v39, v50
	v_and_b32_e32 v50, 0xffff0000, v54
	v_lshlrev_b32_e32 v39, 16, v54
	v_fmac_f32_e32 v50, v33, v51
	v_lshlrev_b32_e32 v51, 16, v55
	v_and_b32_e32 v52, 0xffff0000, v55
	v_fmac_f32_e32 v39, v32, v63
	v_fmac_f32_e32 v51, v34, v64
	v_fmac_f32_e32 v52, v35, v65
	v_cvt_pk_bf16_f32 v32, v66, v36
	v_cvt_pk_bf16_f32 v33, v37, v38
	v_cvt_pk_bf16_f32 v34, v39, v50
	v_cvt_pk_bf16_f32 v35, v51, v52
	global_store_dwordx4 v[56:57], v[32:35], off offset:256
	global_load_dwordx4 v[32:35], v[58:59], off offset:256 nt
	s_waitcnt vmcnt(3)
	v_lshlrev_b32_e32 v36, 16, v42
	v_mul_f32_e32 v36, 0xbfb8aa3b, v36
	v_and_b32_e32 v37, 0xffff0000, v42
	v_exp_f32_e32 v36, v36
	v_mul_f32_e32 v37, 0xbfb8aa3b, v37
	v_exp_f32_e32 v37, v37
	v_and_b32_e32 v38, 0xffff0000, v43
	v_add_f32_e32 v36, 1.0, v36
	v_rcp_f32_e32 v42, v36
	v_add_f32_e32 v36, 1.0, v37
	v_lshlrev_b32_e32 v37, 16, v43
	v_mul_f32_e32 v37, 0xbfb8aa3b, v37
	v_exp_f32_e32 v37, v37
	v_mul_f32_e32 v38, 0xbfb8aa3b, v38
	v_exp_f32_e32 v38, v38
	v_rcp_f32_e32 v43, v36
	v_add_f32_e32 v36, 1.0, v37
	v_rcp_f32_e32 v50, v36
	v_add_f32_e32 v36, 1.0, v38
	v_rcp_f32_e32 v51, v36
	v_lshlrev_b32_e32 v36, 16, v44
	v_mul_f32_e32 v36, 0xbfb8aa3b, v36
	v_and_b32_e32 v37, 0xffff0000, v44
	v_exp_f32_e32 v36, v36
	v_mul_f32_e32 v37, 0xbfb8aa3b, v37
	v_lshlrev_b32_e32 v53, 16, v45
	v_and_b32_e32 v45, 0xffff0000, v45
	v_exp_f32_e32 v44, v37
	v_mul_f32_e32 v53, 0xbfb8aa3b, v53
	v_mul_f32_e32 v45, 0xbfb8aa3b, v45
	v_exp_f32_e32 v53, v53
	v_exp_f32_e32 v45, v45
	v_add_f32_e32 v36, 1.0, v36
	v_rcp_f32_e32 v52, v36
	global_load_dwordx4 v[36:39], v[40:41], off offset:256 nt
	v_add_f32_e32 v44, 1.0, v44
	s_waitcnt vmcnt(3)
	v_lshlrev_b32_e32 v54, 16, v46
	v_rcp_f32_e32 v44, v44
	v_add_f32_e32 v53, 1.0, v53
	v_add_f32_e32 v45, 1.0, v45
	v_fmac_f32_e32 v54, v28, v42
	v_and_b32_e32 v28, 0xffff0000, v46
	v_rcp_f32_e32 v53, v53
	v_rcp_f32_e32 v45, v45
	v_fmac_f32_e32 v28, v29, v43
	v_lshlrev_b32_e32 v29, 16, v47
	v_fmac_f32_e32 v29, v30, v50
	v_and_b32_e32 v30, 0xffff0000, v47
	v_fmac_f32_e32 v30, v31, v51
	v_lshlrev_b32_e32 v31, 16, v48
	v_and_b32_e32 v42, 0xffff0000, v48
	v_fmac_f32_e32 v31, v24, v52
	v_fmac_f32_e32 v42, v25, v44
	v_lshlrev_b32_e32 v43, 16, v49
	v_and_b32_e32 v44, 0xffff0000, v49
	v_cvt_pk_bf16_f32 v24, v54, v28
	v_fmac_f32_e32 v43, v26, v53
	v_fmac_f32_e32 v44, v27, v45
	v_cvt_pk_bf16_f32 v25, v29, v30
	v_cvt_pk_bf16_f32 v26, v31, v42
	v_cvt_pk_bf16_f32 v27, v43, v44
	global_store_dwordx4 v[40:41], v[24:27], off
	v_add_u32_e32 v28, 0xb0, v150
	s_waitcnt vmcnt(2)
	v_lshlrev_b32_e32 v31, 16, v33
	v_lshlrev_b32_e32 v24, 16, v32
	v_mul_f32_e32 v24, 0xbfb8aa3b, v24
	v_exp_f32_e32 v29, v24
	v_and_b32_e32 v24, 0xffff0000, v32
	v_mul_f32_e32 v24, 0xbfb8aa3b, v24
	v_exp_f32_e32 v30, v24
	v_mad_i64_i32 v[24:25], s[0:1], v28, s40, v[152:153]
	v_lshl_add_u64 v[42:43], v[24:25], 0, v[148:149]
	global_load_dwordx4 v[24:27], v[42:43], off nt
	v_mul_f32_e32 v31, 0xbfb8aa3b, v31
	v_and_b32_e32 v32, 0xffff0000, v33
	v_exp_f32_e32 v31, v31
	v_mul_f32_e32 v32, 0xbfb8aa3b, v32
	v_exp_f32_e32 v32, v32
	v_add_f32_e32 v30, 1.0, v30
	v_rcp_f32_e32 v44, v30
	v_add_f32_e32 v30, 1.0, v31
	v_lshlrev_b32_e32 v31, 16, v34
	v_rcp_f32_e32 v45, v30
	v_add_f32_e32 v30, 1.0, v32
	v_mul_f32_e32 v31, 0xbfb8aa3b, v31
	v_and_b32_e32 v32, 0xffff0000, v34
	v_exp_f32_e32 v31, v31
	v_mul_f32_e32 v32, 0xbfb8aa3b, v32
	v_exp_f32_e32 v32, v32
	v_rcp_f32_e32 v34, v30
	v_add_f32_e32 v30, 1.0, v31
	v_lshlrev_b32_e32 v31, 16, v35
	v_rcp_f32_e32 v46, v30
	v_add_f32_e32 v30, 1.0, v32
	v_mul_f32_e32 v31, 0xbfb8aa3b, v31
	v_and_b32_e32 v32, 0xffff0000, v35
	v_add_f32_e32 v29, 1.0, v29
	v_exp_f32_e32 v31, v31
	v_mul_f32_e32 v32, 0xbfb8aa3b, v32
	v_rcp_f32_e32 v29, v29
	v_exp_f32_e32 v32, v32
	v_rcp_f32_e32 v35, v30
	v_add_f32_e32 v30, 1.0, v31
	v_rcp_f32_e32 v47, v30
	v_add_f32_e32 v30, 1.0, v32
	v_rcp_f32_e32 v48, v30
	s_mov_b64 s[0:1], -1
	s_waitcnt vmcnt(2)
	v_lshlrev_b32_e32 v49, 16, v36
	v_fmac_f32_e32 v49, v20, v29
	v_and_b32_e32 v20, 0xffff0000, v36
	v_ashrrev_i32_e32 v29, 31, v28
	v_fmac_f32_e32 v20, v21, v44
	v_lshlrev_b32_e32 v21, 16, v37
	v_lshlrev_b64 v[28:29], 12, v[28:29]
	v_fmac_f32_e32 v21, v22, v45
	v_and_b32_e32 v22, 0xffff0000, v37
	v_lshl_add_u64 v[28:29], s[2:3], 0, v[28:29]
	v_fmac_f32_e32 v22, v23, v34
	v_and_b32_e32 v34, 0xffff0000, v38
	v_lshl_add_u64 v[32:33], v[28:29], 0, v[148:149]
	v_lshlrev_b32_e32 v23, 16, v38
	v_fmac_f32_e32 v34, v17, v35
	v_lshlrev_b32_e32 v35, 16, v39
	v_and_b32_e32 v36, 0xffff0000, v39
	global_load_dwordx4 v[28:31], v[32:33], off nt
	v_fmac_f32_e32 v23, v16, v46
	v_fmac_f32_e32 v35, v18, v47
	v_fmac_f32_e32 v36, v19, v48
	v_cvt_pk_bf16_f32 v16, v49, v20
	v_cvt_pk_bf16_f32 v17, v21, v22
	v_cvt_pk_bf16_f32 v18, v23, v34
	v_cvt_pk_bf16_f32 v19, v35, v36
	global_store_dwordx4 v[40:41], v[16:19], off offset:256
	global_load_dwordx4 v[16:19], v[42:43], off offset:256 nt
	s_waitcnt vmcnt(3)
	v_lshlrev_b32_e32 v20, 16, v24
	v_mul_f32_e32 v20, 0xbfb8aa3b, v20
	v_and_b32_e32 v21, 0xffff0000, v24
	v_exp_f32_e32 v20, v20
	v_mul_f32_e32 v21, 0xbfb8aa3b, v21
	v_exp_f32_e32 v21, v21
	v_and_b32_e32 v22, 0xffff0000, v25
	v_add_f32_e32 v20, 1.0, v20
	v_rcp_f32_e32 v24, v20
	v_add_f32_e32 v20, 1.0, v21
	v_lshlrev_b32_e32 v21, 16, v25
	v_mul_f32_e32 v21, 0xbfb8aa3b, v21
	v_exp_f32_e32 v21, v21
	v_mul_f32_e32 v22, 0xbfb8aa3b, v22
	v_exp_f32_e32 v22, v22
	v_rcp_f32_e32 v25, v20
	v_add_f32_e32 v20, 1.0, v21
	v_rcp_f32_e32 v34, v20
	v_lshlrev_b32_e32 v20, 16, v26
	v_mul_f32_e32 v20, 0xbfb8aa3b, v20
	v_add_f32_e32 v35, 1.0, v22
	v_exp_f32_e32 v36, v20
	global_load_dwordx4 v[20:23], v[32:33], off offset:256 nt
	v_and_b32_e32 v26, 0xffff0000, v26
	v_mul_f32_e32 v26, 0xbfb8aa3b, v26
	v_exp_f32_e32 v26, v26
	v_lshlrev_b32_e32 v37, 16, v27
	v_mul_f32_e32 v37, 0xbfb8aa3b, v37
	v_and_b32_e32 v27, 0xffff0000, v27
	v_exp_f32_e32 v37, v37
	v_mul_f32_e32 v27, 0xbfb8aa3b, v27
	v_rcp_f32_e32 v35, v35
	v_add_f32_e32 v36, 1.0, v36
	v_add_f32_e32 v26, 1.0, v26
	v_exp_f32_e32 v27, v27
	v_rcp_f32_e32 v36, v36
	v_rcp_f32_e32 v26, v26
	v_add_f32_e32 v37, 1.0, v37
	v_rcp_f32_e32 v37, v37
	v_add_f32_e32 v27, 1.0, v27
	v_rcp_f32_e32 v27, v27
	s_waitcnt vmcnt(3)
	v_lshlrev_b32_e32 v38, 16, v28
	v_fmac_f32_e32 v38, v12, v24
	v_and_b32_e32 v12, 0xffff0000, v28
	v_fmac_f32_e32 v12, v13, v25
	v_lshlrev_b32_e32 v13, 16, v29
	v_fmac_f32_e32 v13, v14, v34
	v_and_b32_e32 v14, 0xffff0000, v29
	v_fmac_f32_e32 v14, v15, v35
	v_lshlrev_b32_e32 v15, 16, v30
	v_and_b32_e32 v24, 0xffff0000, v30
	v_fmac_f32_e32 v15, v8, v36
	v_fmac_f32_e32 v24, v9, v26
	v_cvt_pk_bf16_f32 v8, v38, v12
	v_cvt_pk_bf16_f32 v9, v13, v14
	s_waitcnt vmcnt(1)
	v_lshlrev_b32_e32 v12, 16, v16
	v_and_b32_e32 v13, 0xffff0000, v16
	v_mul_f32_e32 v12, 0xbfb8aa3b, v12
	v_mul_f32_e32 v13, 0xbfb8aa3b, v13
	v_lshlrev_b32_e32 v25, 16, v31
	v_exp_f32_e32 v12, v12
	v_exp_f32_e32 v13, v13
	v_fmac_f32_e32 v25, v10, v37
	v_and_b32_e32 v26, 0xffff0000, v31
	v_cvt_pk_bf16_f32 v10, v15, v24
	v_fmac_f32_e32 v26, v11, v27
	v_cvt_pk_bf16_f32 v11, v25, v26
	global_store_dwordx4 v[32:33], v[8:11], off
	v_lshlrev_b32_e32 v14, 16, v19
	v_and_b32_e32 v15, 0xffff0000, v19
	v_lshlrev_b32_e32 v10, 16, v17
	v_mul_f32_e32 v10, 0xbfb8aa3b, v10
	v_and_b32_e32 v11, 0xffff0000, v17
	v_add_f32_e32 v8, 1.0, v12
	v_add_f32_e32 v9, 1.0, v13
	v_exp_f32_e32 v10, v10
	v_mul_f32_e32 v11, 0xbfb8aa3b, v11
	v_lshlrev_b32_e32 v12, 16, v18
	v_and_b32_e32 v13, 0xffff0000, v18
	v_exp_f32_e32 v11, v11
	v_mul_f32_e32 v12, 0xbfb8aa3b, v12
	v_mul_f32_e32 v13, 0xbfb8aa3b, v13
	v_mul_f32_e32 v14, 0xbfb8aa3b, v14
	v_mul_f32_e32 v15, 0xbfb8aa3b, v15
	v_exp_f32_e32 v12, v12
	v_exp_f32_e32 v13, v13
	v_exp_f32_e32 v14, v14
	v_exp_f32_e32 v15, v15
	v_rcp_f32_e32 v8, v8
	v_rcp_f32_e32 v9, v9
	v_add_f32_e32 v10, 1.0, v10
	v_rcp_f32_e32 v10, v10
	v_add_f32_e32 v11, 1.0, v11
	v_rcp_f32_e32 v11, v11
	v_add_f32_e32 v12, 1.0, v12
	v_add_f32_e32 v13, 1.0, v13
	v_add_f32_e32 v14, 1.0, v14
	v_add_f32_e32 v15, 1.0, v15
	s_waitcnt vmcnt(1)
	v_lshlrev_b32_e32 v16, 16, v20
	v_rcp_f32_e32 v12, v12
	v_rcp_f32_e32 v13, v13
	v_rcp_f32_e32 v14, v14
	v_rcp_f32_e32 v15, v15
	v_fmac_f32_e32 v16, v4, v8
	v_and_b32_e32 v4, 0xffff0000, v20
	v_fmac_f32_e32 v4, v5, v9
	v_lshlrev_b32_e32 v5, 16, v21
	v_fmac_f32_e32 v5, v6, v10
	v_and_b32_e32 v6, 0xffff0000, v21
	v_fmac_f32_e32 v6, v7, v11
	v_lshlrev_b32_e32 v7, 16, v22
	v_and_b32_e32 v8, 0xffff0000, v22
	v_lshlrev_b32_e32 v9, 16, v23
	v_and_b32_e32 v10, 0xffff0000, v23
	v_fmac_f32_e32 v7, v0, v12
	v_fmac_f32_e32 v8, v1, v13
	v_fmac_f32_e32 v9, v2, v14
	v_fmac_f32_e32 v10, v3, v15
	v_cvt_pk_bf16_f32 v0, v16, v4
	v_cvt_pk_bf16_f32 v1, v5, v6
	v_cvt_pk_bf16_f32 v2, v7, v8
	v_cvt_pk_bf16_f32 v3, v9, v10
	global_store_dwordx4 v[32:33], v[0:3], off offset:256
	s_cbranch_vccnz .LBB0_858
	s_andn2_b64 vcc, exec, s[10:11]
	s_cbranch_vccnz .LBB0_857
	s_barrier
	s_branch .LBB0_857
